# GEMM K-loops: dropped the redundant post-barrier lgkmcnt(0) and the mid-block setprio 0/1 flip pairs
# speedup vs baseline: 1.0036x; 1.0036x over previous
; #define PG8_STAGE(bufoff, gbase, voff) do { _Pragma("unroll") for (int _i = 0; _i < 2; ++_i) \
;         __builtin_amdgcn_global_load_lds((const unsigned*)((const char*)(gbase) + (voff)[_i]), (PG8_LAS unsigned*)(lds + (bufoff) + ldsw + _i * 8192), 16, 0, 0); } while (0)
; #define PG8_LDA(dst, b, h) do { _Pragma("unroll") for (int m = 0; m < 4; ++m) _Pragma("unroll") for (int k = 0; k < 2; ++k) dst[m][k] = *(const PG8_LAS bf16x8*)(lds + PG8_SA(b, h) + aoff + m * 2048 + k * 1024); } while (0)
; #define PG8_LDB(dst, b, h) do { _Pragma("unroll") for (int n = 0; n < 2; ++n) _Pragma("unroll") for (int k = 0; k < 2; ++k) dst[n][k] = *(const PG8_LAS bf16x8*)(lds + PG8_SB(b, h) + boff + n * 2048 + k * 1024); } while (0)
; #define PG8_MMA(ai, bj, At, Bt) do { __builtin_amdgcn_s_setprio(1); _Pragma("unroll") for (int m = 0; m < 4; ++m) _Pragma("unroll") for (int n = 0; n < 2; ++n) _Pragma("unroll") for (int k = 0; k < 2; ++k) \
;         acc[ai][bj][m][n] = __builtin_amdgcn_mfma_f32_16x16x32_bf16(Bt[n][k], At[m][k], acc[ai][bj][m][n], 0, 0, 0); __builtin_amdgcn_s_setprio(0); } while (0)
; #define PG8_WAIT_V(n) asm volatile("s_waitcnt vmcnt(" #n ")" ::: "memory")
; #define PG8_WAIT_L(n) asm volatile("s_waitcnt lgkmcnt(" #n ")" ::: "memory")
; template <class Epi, class Sched, bool ALIGN_EPI = false, bool SP2 = false>
; __device__ __forceinline__ void gemm_phase(PG8_LAS unsigned char* lds, const Gemm g, const Sched& S, const Epi& E, const int tid_in) {
;     ...
;             const bool last = (t == nt - 2);
;             const char* a1 = cA + (size_t)(t + 1) * kstep;
;             const char* a2 = last ? nA : cA + (size_t)(t + 2) * kstep; const char* b2 = last ? nB : cB + (size_t)(t + 2) * kstep;
;             const char* a3 = a2 + kstep; const char* b3 = b2 + kstep;
;             if (last && has_next) S.a_ready(nxt);
;             if constexpr (SP2) {
;             PG8_LDB(B0, 0, 0); PG8_LDB(B1, 0, 1); PG8_SCHED; PG8_LDA(At, 0, 0); PG8_STAGE(PG8_SA(1, 1), a1 + hstep, voffA);
;             PG8_WAIT_V(8); PG8_WAIT_L(0); PG8_BAR; PG8_MMA(0, 0, At, B0); PG8_MMA(0, 1, At, B1); PG8_BAR; PG8_SCHED;
;             PG8_LDA(At, 0, 1); PG8_STAGE(PG8_SB(0, 0), b2, voffB); PG8_STAGE(PG8_SB(0, 1), b2 + hstep, voffB); PG8_STAGE(PG8_SA(0, 0), a2, voffA);
;             PG8_WAIT_V(8); PG8_WAIT_L(0); PG8_BAR; PG8_MMA(1, 0, At, B0); PG8_MMA(1, 1, At, B1); PG8_BAR; PG8_SCHED;
.LBB0_220:
	ds_read_b128 v[152:155], v182
	ds_read_b128 v[156:159], v182 offset:1024
	ds_read_b128 v[160:163], v182 offset:2048
	ds_read_b128 v[164:167], v182 offset:3072
	ds_read_b128 v[168:171], v183
	ds_read_b128 v[172:175], v183 offset:1024
	ds_read_b128 v[176:179], v183 offset:2048
	ds_read_b128 v[186:189], v183 offset:3072
	s_add_u32 s14, s12, 0xfff00080
	s_addc_u32 s15, s13, -1
	s_cmp_eq_u32 s22, 60
	s_cselect_b32 s17, s1, s15
	s_cselect_b32 s16, s6, s14
	s_cselect_b32 s15, s7, s21
	s_cselect_b32 s14, s11, s20
	v_lshl_add_u64 v[222:223], s[12:13], 0, v[144:145]
	s_add_i32 m0, s39, 0xc000
	ds_read_b128 v[190:193], v184
	ds_read_b128 v[194:197], v184 offset:1024
	ds_read_b128 v[198:201], v184 offset:2048
	ds_read_b128 v[202:205], v184 offset:3072
	ds_read_b128 v[206:209], v184 offset:4096
	ds_read_b128 v[210:213], v184 offset:5120
	ds_read_b128 v[214:217], v184 offset:6144
	ds_read_b128 v[218:221], v184 offset:7168
	global_load_lds_dwordx4 v[222:223], off
	v_lshl_add_u64 v[222:223], s[12:13], 0, v[146:147]
	s_add_i32 m0, s39, 0xe000
	s_nop 0
	global_load_lds_dwordx4 v[222:223], off
	s_waitcnt vmcnt(8)
	s_waitcnt lgkmcnt(0)
	s_barrier
	s_setprio 1
	v_mfma_f32_16x16x32_bf16 v[124:127], v[152:155], v[190:193], v[124:127]
	v_mfma_f32_16x16x32_bf16 v[120:123], v[160:163], v[190:193], v[120:123]
	v_mfma_f32_16x16x32_bf16 v[108:111], v[152:155], v[198:201], v[108:111]
	v_mfma_f32_16x16x32_bf16 v[104:107], v[160:163], v[198:201], v[104:107]
	v_mfma_f32_16x16x32_bf16 v[92:95], v[152:155], v[206:209], v[92:95]
	v_mfma_f32_16x16x32_bf16 v[88:91], v[160:163], v[206:209], v[88:91]
	v_mfma_f32_16x16x32_bf16 v[76:79], v[152:155], v[214:217], v[76:79]
	v_mfma_f32_16x16x32_bf16 v[72:75], v[160:163], v[214:217], v[72:75]
	v_mfma_f32_16x16x32_bf16 v[124:127], v[156:159], v[194:197], v[124:127]
	v_mfma_f32_16x16x32_bf16 v[120:123], v[164:167], v[194:197], v[120:123]
	v_mfma_f32_16x16x32_bf16 v[108:111], v[156:159], v[202:205], v[108:111]
	v_mfma_f32_16x16x32_bf16 v[104:107], v[164:167], v[202:205], v[104:107]
	v_mfma_f32_16x16x32_bf16 v[92:95], v[156:159], v[210:213], v[92:95]
	v_mfma_f32_16x16x32_bf16 v[88:91], v[164:167], v[210:213], v[88:91]
	v_mfma_f32_16x16x32_bf16 v[76:79], v[156:159], v[218:221], v[76:79]
	v_mfma_f32_16x16x32_bf16 v[72:75], v[164:167], v[218:221], v[72:75]
	v_mfma_f32_16x16x32_bf16 v[116:119], v[168:171], v[190:193], v[116:119]
	v_mfma_f32_16x16x32_bf16 v[112:115], v[176:179], v[190:193], v[112:115]
	v_mfma_f32_16x16x32_bf16 v[100:103], v[168:171], v[198:201], v[100:103]
	v_mfma_f32_16x16x32_bf16 v[96:99], v[176:179], v[198:201], v[96:99]
	v_mfma_f32_16x16x32_bf16 v[84:87], v[168:171], v[206:209], v[84:87]
	v_mfma_f32_16x16x32_bf16 v[80:83], v[176:179], v[206:209], v[80:83]
	v_mfma_f32_16x16x32_bf16 v[68:71], v[168:171], v[214:217], v[68:71]
	v_mfma_f32_16x16x32_bf16 v[64:67], v[176:179], v[214:217], v[64:67]
	v_mfma_f32_16x16x32_bf16 v[116:119], v[172:175], v[194:197], v[116:119]
	v_mfma_f32_16x16x32_bf16 v[112:115], v[186:189], v[194:197], v[112:115]
	v_mfma_f32_16x16x32_bf16 v[100:103], v[172:175], v[202:205], v[100:103]
	v_mfma_f32_16x16x32_bf16 v[96:99], v[186:189], v[202:205], v[96:99]
	v_mfma_f32_16x16x32_bf16 v[84:87], v[172:175], v[210:213], v[84:87]
	v_mfma_f32_16x16x32_bf16 v[80:83], v[186:189], v[210:213], v[80:83]
	v_mfma_f32_16x16x32_bf16 v[68:71], v[172:175], v[218:221], v[68:71]
	v_mfma_f32_16x16x32_bf16 v[64:67], v[186:189], v[218:221], v[64:67]
	s_setprio 0
	s_barrier
	s_add_i32 s23, s3, s38
	v_lshl_add_u64 v[222:223], s[14:15], 0, v[130:131]
	s_mov_b32 m0, s23
	ds_read_b128 v[190:193], v184 offset:16384
	ds_read_b128 v[194:197], v184 offset:17408
	ds_read_b128 v[198:201], v184 offset:18432
	ds_read_b128 v[202:205], v184 offset:19456
	ds_read_b128 v[206:209], v184 offset:20480
	ds_read_b128 v[210:213], v184 offset:21504
	ds_read_b128 v[214:217], v184 offset:22528
	ds_read_b128 v[218:221], v184 offset:23552
	global_load_lds_dwordx4 v[222:223], off
	s_add_i32 m0, s23, 0x2000
	s_add_u32 s62, s14, 0x100000
	v_lshl_add_u64 v[224:225], s[14:15], 0, v[134:135]
	s_addc_u32 s63, s15, 0
	s_add_i32 s23, s28, s38
	global_load_lds_dwordx4 v[224:225], off
	v_lshl_add_u64 v[226:227], s[62:63], 0, v[130:131]
	s_mov_b32 m0, s23
	v_lshl_add_u64 v[228:229], s[16:17], 0, v[132:133]
	global_load_lds_dwordx4 v[226:227], off
	v_lshl_add_u64 v[226:227], s[62:63], 0, v[134:135]
	s_add_i32 m0, s23, 0x2000
	s_nop 0
	global_load_lds_dwordx4 v[226:227], off
	v_lshl_add_u64 v[226:227], s[16:17], 0, v[128:129]
	s_mov_b32 m0, s39
	s_nop 0
	global_load_lds_dwordx4 v[226:227], off
	s_mov_b32 m0, s24
	s_nop 0
	global_load_lds_dwordx4 v[228:229], off
	s_waitcnt vmcnt(8)
	s_waitcnt lgkmcnt(0)
	s_barrier
; #define PG8_STAGE(bufoff, gbase, voff) do { _Pragma("unroll") for (int _i = 0; _i < 2; ++_i) \
;         __builtin_amdgcn_global_load_lds((const unsigned*)((const char*)(gbase) + (voff)[_i]), (PG8_LAS unsigned*)(lds + (bufoff) + ldsw + _i * 8192), 16, 0, 0); } while (0)
; #define PG8_LDA(dst, b, h) do { _Pragma("unroll") for (int m = 0; m < 4; ++m) _Pragma("unroll") for (int k = 0; k < 2; ++k) dst[m][k] = *(const PG8_LAS bf16x8*)(lds + PG8_SA(b, h) + aoff + m * 2048 + k * 1024); } while (0)
; #define PG8_LDB(dst, b, h) do { _Pragma("unroll") for (int n = 0; n < 2; ++n) _Pragma("unroll") for (int k = 0; k < 2; ++k) dst[n][k] = *(const PG8_LAS bf16x8*)(lds + PG8_SB(b, h) + boff + n * 2048 + k * 1024); } while (0)
; #define PG8_MMA(ai, bj, At, Bt) do { __builtin_amdgcn_s_setprio(1); _Pragma("unroll") for (int m = 0; m < 4; ++m) _Pragma("unroll") for (int n = 0; n < 2; ++n) _Pragma("unroll") for (int k = 0; k < 2; ++k) \
;         acc[ai][bj][m][n] = __builtin_amdgcn_mfma_f32_16x16x32_bf16(Bt[n][k], At[m][k], acc[ai][bj][m][n], 0, 0, 0); __builtin_amdgcn_s_setprio(0); } while (0)
; #define PG8_WAIT_V(n) asm volatile("s_waitcnt vmcnt(" #n ")" ::: "memory")
; #define PG8_WAIT_L(n) asm volatile("s_waitcnt lgkmcnt(" #n ")" ::: "memory")
; #define PG8_BAR __builtin_amdgcn_s_barrier()
; #define PG8_SCHED __builtin_amdgcn_sched_barrier(0)
; template <class Epi, class Sched, bool ALIGN_EPI = false, bool SP2 = false>
; __device__ __forceinline__ void gemm_phase(PG8_LAS unsigned char* lds, const Gemm g, const Sched& S, const Epi& E, const int tid_in) {
;     ...
;             PG8_WAIT_V(8); PG8_WAIT_L(0); PG8_BAR; PG8_MMA(1, 0, At, B0); PG8_MMA(1, 1, At, B1); PG8_BAR; PG8_SCHED;
;             PG8_LDB(B0, 1, 0); PG8_LDB(B1, 1, 1); PG8_SCHED; PG8_LDA(At, 1, 0); PG8_STAGE(PG8_SA(0, 1), a2 + hstep, voffA);
;             PG8_WAIT_V(8); PG8_WAIT_L(0); PG8_BAR; PG8_MMA(0, 0, At, B0); PG8_MMA(0, 1, At, B1); PG8_BAR; PG8_SCHED;
	s_setprio 1
	v_mfma_f32_16x16x32_bf16 v[60:63], v[152:155], v[190:193], v[60:63]
	v_mfma_f32_16x16x32_bf16 v[56:59], v[160:163], v[190:193], v[56:59]
	v_mfma_f32_16x16x32_bf16 v[44:47], v[152:155], v[198:201], v[44:47]
	v_mfma_f32_16x16x32_bf16 v[40:43], v[160:163], v[198:201], v[40:43]
	v_mfma_f32_16x16x32_bf16 v[28:31], v[152:155], v[206:209], v[28:31]
	v_mfma_f32_16x16x32_bf16 v[24:27], v[160:163], v[206:209], v[24:27]
	v_mfma_f32_16x16x32_bf16 v[12:15], v[152:155], v[214:217], v[12:15]
	v_mfma_f32_16x16x32_bf16 v[8:11], v[160:163], v[214:217], v[8:11]
	v_mfma_f32_16x16x32_bf16 v[60:63], v[156:159], v[194:197], v[60:63]
	v_mfma_f32_16x16x32_bf16 v[56:59], v[164:167], v[194:197], v[56:59]
	v_mfma_f32_16x16x32_bf16 v[44:47], v[156:159], v[202:205], v[44:47]
	v_mfma_f32_16x16x32_bf16 v[40:43], v[164:167], v[202:205], v[40:43]
	v_mfma_f32_16x16x32_bf16 v[28:31], v[156:159], v[210:213], v[28:31]
	v_mfma_f32_16x16x32_bf16 v[24:27], v[164:167], v[210:213], v[24:27]
	v_mfma_f32_16x16x32_bf16 v[12:15], v[156:159], v[218:221], v[12:15]
	v_mfma_f32_16x16x32_bf16 v[8:11], v[164:167], v[218:221], v[8:11]
	v_mfma_f32_16x16x32_bf16 v[52:55], v[168:171], v[190:193], v[52:55]
	v_mfma_f32_16x16x32_bf16 v[48:51], v[176:179], v[190:193], v[48:51]
	v_mfma_f32_16x16x32_bf16 v[36:39], v[168:171], v[198:201], v[36:39]
	v_mfma_f32_16x16x32_bf16 v[32:35], v[176:179], v[198:201], v[32:35]
	v_mfma_f32_16x16x32_bf16 v[20:23], v[168:171], v[206:209], v[20:23]
	v_mfma_f32_16x16x32_bf16 v[16:19], v[176:179], v[206:209], v[16:19]
	v_mfma_f32_16x16x32_bf16 v[4:7], v[168:171], v[214:217], v[4:7]
	v_mfma_f32_16x16x32_bf16 v[0:3], v[176:179], v[214:217], v[0:3]
	v_mfma_f32_16x16x32_bf16 v[52:55], v[172:175], v[194:197], v[52:55]
	v_mfma_f32_16x16x32_bf16 v[48:51], v[186:189], v[194:197], v[48:51]
	v_mfma_f32_16x16x32_bf16 v[36:39], v[172:175], v[202:205], v[36:39]
	v_mfma_f32_16x16x32_bf16 v[32:35], v[186:189], v[202:205], v[32:35]
	v_mfma_f32_16x16x32_bf16 v[20:23], v[172:175], v[210:213], v[20:23]
	v_mfma_f32_16x16x32_bf16 v[16:19], v[186:189], v[210:213], v[16:19]
	v_mfma_f32_16x16x32_bf16 v[4:7], v[172:175], v[218:221], v[4:7]
	v_mfma_f32_16x16x32_bf16 v[0:3], v[186:189], v[218:221], v[0:3]
	s_setprio 0
	s_barrier
	s_add_i32 s23, 0, 0x18000
	v_add_u32_e32 v136, s23, v181
	s_add_i32 s26, 0, 0x1c000
	ds_read_b128 v[152:155], v136
	ds_read_b128 v[156:159], v136 offset:1024
	ds_read_b128 v[160:163], v136 offset:2048
	ds_read_b128 v[164:167], v136 offset:3072
	v_add_u32_e32 v136, s26, v181
	ds_read_b128 v[168:171], v136
	ds_read_b128 v[172:175], v136 offset:1024
	ds_read_b128 v[176:179], v136 offset:2048
	ds_read_b128 v[186:189], v136 offset:3072
	s_add_u32 s16, s16, 0x100000
	s_addc_u32 s17, s17, 0
	s_mov_b32 m0, s25
	v_lshl_add_u64 v[230:231], s[16:17], 0, v[128:129]
	ds_read_b128 v[190:193], v184 offset:32768
	ds_read_b128 v[194:197], v184 offset:33792
	ds_read_b128 v[198:201], v184 offset:34816
	ds_read_b128 v[202:205], v184 offset:35840
	ds_read_b128 v[206:209], v184 offset:36864
	ds_read_b128 v[210:213], v184 offset:37888
	ds_read_b128 v[214:217], v184 offset:38912
	ds_read_b128 v[218:221], v184 offset:39936
	global_load_lds_dwordx4 v[230:231], off
	v_lshl_add_u64 v[230:231], s[16:17], 0, v[132:133]
	s_mov_b32 m0, s36
	s_nop 0
	global_load_lds_dwordx4 v[230:231], off
	s_waitcnt vmcnt(8)
	s_waitcnt lgkmcnt(0)
	s_barrier
	s_setprio 1
	v_mfma_f32_16x16x32_bf16 v[124:127], v[152:155], v[190:193], v[124:127]
	v_mfma_f32_16x16x32_bf16 v[120:123], v[160:163], v[190:193], v[120:123]
	v_mfma_f32_16x16x32_bf16 v[108:111], v[152:155], v[198:201], v[108:111]
	v_mfma_f32_16x16x32_bf16 v[104:107], v[160:163], v[198:201], v[104:107]
	v_mfma_f32_16x16x32_bf16 v[92:95], v[152:155], v[206:209], v[92:95]
	v_mfma_f32_16x16x32_bf16 v[88:91], v[160:163], v[206:209], v[88:91]
	v_mfma_f32_16x16x32_bf16 v[76:79], v[152:155], v[214:217], v[76:79]
	v_mfma_f32_16x16x32_bf16 v[72:75], v[160:163], v[214:217], v[72:75]
	v_mfma_f32_16x16x32_bf16 v[124:127], v[156:159], v[194:197], v[124:127]
	v_mfma_f32_16x16x32_bf16 v[120:123], v[164:167], v[194:197], v[120:123]
	v_mfma_f32_16x16x32_bf16 v[108:111], v[156:159], v[202:205], v[108:111]
	v_mfma_f32_16x16x32_bf16 v[104:107], v[164:167], v[202:205], v[104:107]
	v_mfma_f32_16x16x32_bf16 v[92:95], v[156:159], v[210:213], v[92:95]
	v_mfma_f32_16x16x32_bf16 v[88:91], v[164:167], v[210:213], v[88:91]
	v_mfma_f32_16x16x32_bf16 v[76:79], v[156:159], v[218:221], v[76:79]
	v_mfma_f32_16x16x32_bf16 v[72:75], v[164:167], v[218:221], v[72:75]
	v_mfma_f32_16x16x32_bf16 v[116:119], v[168:171], v[190:193], v[116:119]
	v_mfma_f32_16x16x32_bf16 v[112:115], v[176:179], v[190:193], v[112:115]
	v_mfma_f32_16x16x32_bf16 v[100:103], v[168:171], v[198:201], v[100:103]
	v_mfma_f32_16x16x32_bf16 v[96:99], v[176:179], v[198:201], v[96:99]
	v_mfma_f32_16x16x32_bf16 v[84:87], v[168:171], v[206:209], v[84:87]
	v_mfma_f32_16x16x32_bf16 v[80:83], v[176:179], v[206:209], v[80:83]
	v_mfma_f32_16x16x32_bf16 v[68:71], v[168:171], v[214:217], v[68:71]
	v_mfma_f32_16x16x32_bf16 v[64:67], v[176:179], v[214:217], v[64:67]
	v_mfma_f32_16x16x32_bf16 v[116:119], v[172:175], v[194:197], v[116:119]
	v_mfma_f32_16x16x32_bf16 v[112:115], v[186:189], v[194:197], v[112:115]
	v_mfma_f32_16x16x32_bf16 v[100:103], v[172:175], v[202:205], v[100:103]
	v_mfma_f32_16x16x32_bf16 v[96:99], v[186:189], v[202:205], v[96:99]
	v_mfma_f32_16x16x32_bf16 v[84:87], v[172:175], v[210:213], v[84:87]
	v_mfma_f32_16x16x32_bf16 v[80:83], v[186:189], v[210:213], v[80:83]
	v_mfma_f32_16x16x32_bf16 v[68:71], v[172:175], v[218:221], v[68:71]
	v_mfma_f32_16x16x32_bf16 v[64:67], v[186:189], v[218:221], v[64:67]
	s_setprio 0
	s_barrier
; #define PG8_STAGE(bufoff, gbase, voff) do { _Pragma("unroll") for (int _i = 0; _i < 2; ++_i) \
;         __builtin_amdgcn_global_load_lds((const unsigned*)((const char*)(gbase) + (voff)[_i]), (PG8_LAS unsigned*)(lds + (bufoff) + ldsw + _i * 8192), 16, 0, 0); } while (0)
; #define PG8_LDA(dst, b, h) do { _Pragma("unroll") for (int m = 0; m < 4; ++m) _Pragma("unroll") for (int k = 0; k < 2; ++k) dst[m][k] = *(const PG8_LAS bf16x8*)(lds + PG8_SA(b, h) + aoff + m * 2048 + k * 1024); } while (0)
; #define PG8_MMA(ai, bj, At, Bt) do { __builtin_amdgcn_s_setprio(1); _Pragma("unroll") for (int m = 0; m < 4; ++m) _Pragma("unroll") for (int n = 0; n < 2; ++n) _Pragma("unroll") for (int k = 0; k < 2; ++k) \
;         acc[ai][bj][m][n] = __builtin_amdgcn_mfma_f32_16x16x32_bf16(Bt[n][k], At[m][k], acc[ai][bj][m][n], 0, 0, 0); __builtin_amdgcn_s_setprio(0); } while (0)
; #define PG8_WAIT_V(n) asm volatile("s_waitcnt vmcnt(" #n ")" ::: "memory")
; #define PG8_WAIT_L(n) asm volatile("s_waitcnt lgkmcnt(" #n ")" ::: "memory")
; #define PG8_BAR __builtin_amdgcn_s_barrier()
; #define PG8_SCHED __builtin_amdgcn_sched_barrier(0)
; template <class Epi, class Sched, bool ALIGN_EPI = false, bool SP2 = false>
; __device__ __forceinline__ void gemm_phase(PG8_LAS unsigned char* lds, const Gemm g, const Sched& S, const Epi& E, const int tid_in) {
;     ...
;         for (int t = 0; t < nt; t += 2) {
;     ...
;             PG8_LDA(At, 1, 1); PG8_STAGE(PG8_SB(1, 0), b3, voffB); PG8_STAGE(PG8_SB(1, 1), b3 + hstep, voffB); PG8_STAGE(PG8_SA(1, 0), a3, voffA);
;             PG8_WAIT_V(8); PG8_WAIT_L(0); PG8_BAR; PG8_MMA(1, 0, At, B0); PG8_MMA(1, 1, At, B1); PG8_BAR; PG8_SCHED;
	s_add_i32 s16, s23, s38
	v_lshl_add_u64 v[222:223], v[222:223], 0, s[30:31]
	s_mov_b32 m0, s16
	ds_read_b128 v[190:193], v184 offset:49152
	ds_read_b128 v[194:197], v184 offset:50176
	ds_read_b128 v[198:201], v184 offset:51200
	ds_read_b128 v[202:205], v184 offset:52224
	ds_read_b128 v[206:209], v184 offset:53248
	ds_read_b128 v[210:213], v184 offset:54272
	ds_read_b128 v[214:217], v184 offset:55296
	ds_read_b128 v[218:221], v184 offset:56320
	global_load_lds_dwordx4 v[222:223], off
	s_add_i32 m0, s16, 0x2000
	s_add_u32 s14, s14, 0x100080
	v_lshl_add_u64 v[222:223], v[224:225], 0, s[30:31]
	s_addc_u32 s15, s15, 0
	s_add_i32 s16, s26, s38
	global_load_lds_dwordx4 v[222:223], off
	v_lshl_add_u64 v[222:223], s[14:15], 0, v[130:131]
	s_mov_b32 m0, s16
	s_nop 0
	global_load_lds_dwordx4 v[222:223], off
	v_lshl_add_u64 v[222:223], s[14:15], 0, v[134:135]
	s_add_i32 m0, s16, 0x2000
	s_nop 0
	global_load_lds_dwordx4 v[222:223], off
	v_lshl_add_u64 v[222:223], v[226:227], 0, s[30:31]
	s_mov_b32 m0, s29
	s_nop 0
	global_load_lds_dwordx4 v[222:223], off
	v_lshl_add_u64 v[222:223], v[228:229], 0, s[30:31]
	s_mov_b32 m0, s2
	s_nop 0
	global_load_lds_dwordx4 v[222:223], off
	s_waitcnt vmcnt(8)
	s_waitcnt lgkmcnt(0)
	s_barrier
	s_setprio 1
	v_mfma_f32_16x16x32_bf16 v[60:63], v[152:155], v[190:193], v[60:63]
	v_mfma_f32_16x16x32_bf16 v[56:59], v[160:163], v[190:193], v[56:59]
	v_mfma_f32_16x16x32_bf16 v[44:47], v[152:155], v[198:201], v[44:47]
	v_mfma_f32_16x16x32_bf16 v[40:43], v[160:163], v[198:201], v[40:43]
	v_mfma_f32_16x16x32_bf16 v[28:31], v[152:155], v[206:209], v[28:31]
	v_mfma_f32_16x16x32_bf16 v[24:27], v[160:163], v[206:209], v[24:27]
	v_mfma_f32_16x16x32_bf16 v[12:15], v[152:155], v[214:217], v[12:15]
	v_mfma_f32_16x16x32_bf16 v[8:11], v[160:163], v[214:217], v[8:11]
	v_mfma_f32_16x16x32_bf16 v[60:63], v[156:159], v[194:197], v[60:63]
	v_mfma_f32_16x16x32_bf16 v[56:59], v[164:167], v[194:197], v[56:59]
	v_mfma_f32_16x16x32_bf16 v[44:47], v[156:159], v[202:205], v[44:47]
	v_mfma_f32_16x16x32_bf16 v[40:43], v[164:167], v[202:205], v[40:43]
	v_mfma_f32_16x16x32_bf16 v[28:31], v[156:159], v[210:213], v[28:31]
	v_mfma_f32_16x16x32_bf16 v[24:27], v[164:167], v[210:213], v[24:27]
	v_mfma_f32_16x16x32_bf16 v[12:15], v[156:159], v[218:221], v[12:15]
	v_mfma_f32_16x16x32_bf16 v[8:11], v[164:167], v[218:221], v[8:11]
	v_mfma_f32_16x16x32_bf16 v[52:55], v[168:171], v[190:193], v[52:55]
	v_mfma_f32_16x16x32_bf16 v[48:51], v[176:179], v[190:193], v[48:51]
	v_mfma_f32_16x16x32_bf16 v[36:39], v[168:171], v[198:201], v[36:39]
	v_mfma_f32_16x16x32_bf16 v[32:35], v[176:179], v[198:201], v[32:35]
	v_mfma_f32_16x16x32_bf16 v[20:23], v[168:171], v[206:209], v[20:23]
	v_mfma_f32_16x16x32_bf16 v[16:19], v[176:179], v[206:209], v[16:19]
	v_mfma_f32_16x16x32_bf16 v[4:7], v[168:171], v[214:217], v[4:7]
	v_mfma_f32_16x16x32_bf16 v[0:3], v[176:179], v[214:217], v[0:3]
	v_mfma_f32_16x16x32_bf16 v[52:55], v[172:175], v[194:197], v[52:55]
	v_mfma_f32_16x16x32_bf16 v[48:51], v[186:189], v[194:197], v[48:51]
	v_mfma_f32_16x16x32_bf16 v[36:39], v[172:175], v[202:205], v[36:39]
	v_mfma_f32_16x16x32_bf16 v[32:35], v[186:189], v[202:205], v[32:35]
	v_mfma_f32_16x16x32_bf16 v[20:23], v[172:175], v[210:213], v[20:23]
	v_mfma_f32_16x16x32_bf16 v[16:19], v[186:189], v[210:213], v[16:19]
	v_mfma_f32_16x16x32_bf16 v[4:7], v[172:175], v[218:221], v[4:7]
	v_mfma_f32_16x16x32_bf16 v[0:3], v[186:189], v[218:221], v[0:3]
	s_setprio 0
	s_barrier
	s_add_i32 s22, s22, 2
	s_add_u32 s12, s12, 0x100
	s_addc_u32 s13, s13, 0
	s_add_u32 s20, s20, 0x100
	s_addc_u32 s21, s21, 0
	s_cmp_gt_u32 s22, 61
	s_cbranch_scc0 .LBB0_220
	v_readlane_b32 s4, v250, 30
	v_readlane_b32 s5, v250, 31
	s_and_b64 vcc, exec, s[4:5]
	s_cbranch_vccz .LBB0_223
	s_barrier

; #define PG8_STAGE(bufoff, gbase, voff) do { _Pragma("unroll") for (int _i = 0; _i < 2; ++_i) \
;         __builtin_amdgcn_global_load_lds((const unsigned*)((const char*)(gbase) + (voff)[_i]), (PG8_LAS unsigned*)(lds + (bufoff) + ldsw + _i * 8192), 16, 0, 0); } while (0)
; #define PG8_LDA(dst, b, h) do { _Pragma("unroll") for (int m = 0; m < 4; ++m) _Pragma("unroll") for (int k = 0; k < 2; ++k) dst[m][k] = *(const PG8_LAS bf16x8*)(lds + PG8_SA(b, h) + aoff + m * 2048 + k * 1024); } while (0)
; #define PG8_LDB(dst, b, h) do { _Pragma("unroll") for (int n = 0; n < 2; ++n) _Pragma("unroll") for (int k = 0; k < 2; ++k) dst[n][k] = *(const PG8_LAS bf16x8*)(lds + PG8_SB(b, h) + boff + n * 2048 + k * 1024); } while (0)
; #define PG8_MMA(ai, bj, At, Bt) do { __builtin_amdgcn_s_setprio(1); _Pragma("unroll") for (int m = 0; m < 4; ++m) _Pragma("unroll") for (int n = 0; n < 2; ++n) _Pragma("unroll") for (int k = 0; k < 2; ++k) \
;         acc[ai][bj][m][n] = __builtin_amdgcn_mfma_f32_16x16x32_bf16(Bt[n][k], At[m][k], acc[ai][bj][m][n], 0, 0, 0); __builtin_amdgcn_s_setprio(0); } while (0)
; #define PG8_WAIT_V(n) asm volatile("s_waitcnt vmcnt(" #n ")" ::: "memory")
; #define PG8_WAIT_L(n) asm volatile("s_waitcnt lgkmcnt(" #n ")" ::: "memory")
; template <class Epi, class Sched, bool ALIGN_EPI = false, bool SP2 = false>
; __device__ __forceinline__ void gemm_phase(PG8_LAS unsigned char* lds, const Gemm g, const Sched& S, const Epi& E, const int tid_in) {
;     ...
;             const bool last = (t == nt - 2);
;             const char* a1 = cA + (size_t)(t + 1) * kstep;
;             const char* a2 = last ? nA : cA + (size_t)(t + 2) * kstep; const char* b2 = last ? nB : cB + (size_t)(t + 2) * kstep;
;             const char* a3 = a2 + kstep; const char* b3 = b2 + kstep;
;             if (last && has_next) S.a_ready(nxt);
;             if constexpr (SP2) {
;             PG8_LDB(B0, 0, 0); PG8_LDB(B1, 0, 1); PG8_SCHED; PG8_LDA(At, 0, 0); PG8_STAGE(PG8_SA(1, 1), a1 + hstep, voffA);
;             PG8_WAIT_V(8); PG8_WAIT_L(0); PG8_BAR; PG8_MMA(0, 0, At, B0); PG8_MMA(0, 1, At, B1); PG8_BAR; PG8_SCHED;
;             PG8_LDA(At, 0, 1); PG8_STAGE(PG8_SB(0, 0), b2, voffB); PG8_STAGE(PG8_SB(0, 1), b2 + hstep, voffB); PG8_STAGE(PG8_SA(0, 0), a2, voffA);
;             PG8_WAIT_V(8); PG8_WAIT_L(0); PG8_BAR; PG8_MMA(1, 0, At, B0); PG8_MMA(1, 1, At, B1); PG8_BAR; PG8_SCHED;
.LBB0_1613:
	ds_read_b128 v[128:131], v171
	ds_read_b128 v[132:135], v171 offset:1024
	ds_read_b128 v[136:139], v171 offset:2048
	ds_read_b128 v[140:143], v171 offset:3072
	ds_read_b128 v[160:163], v172
	ds_read_b128 v[174:177], v172 offset:1024
	ds_read_b128 v[178:181], v172 offset:2048
	ds_read_b128 v[182:185], v172 offset:3072
	s_add_u32 s28, s26, 0xfff00080
	s_addc_u32 s29, s27, -1
	s_cmp_eq_u32 s55, 60
	s_cselect_b32 s31, s19, s29
	s_cselect_b32 s30, s51, s28
	s_cselect_b32 s29, s17, s54
	s_cselect_b32 s28, s52, s53
	v_lshl_add_u64 v[164:165], s[26:27], 0, v[152:153]
	s_add_i32 m0, s25, 0xc000
	ds_read_b128 v[186:189], v173
	ds_read_b128 v[190:193], v173 offset:1024
	ds_read_b128 v[194:197], v173 offset:2048
	ds_read_b128 v[198:201], v173 offset:3072
	ds_read_b128 v[202:205], v173 offset:4096
	ds_read_b128 v[206:209], v173 offset:5120
	ds_read_b128 v[210:213], v173 offset:6144
	ds_read_b128 v[214:217], v173 offset:7168
	global_load_lds_dwordx4 v[164:165], off
	v_lshl_add_u64 v[164:165], s[26:27], 0, v[154:155]
	s_add_i32 m0, s25, 0xe000
	s_nop 0
	global_load_lds_dwordx4 v[164:165], off
	s_waitcnt vmcnt(8)
	s_waitcnt lgkmcnt(0)
	s_barrier
	s_setprio 1
	v_mfma_f32_16x16x32_bf16 v[124:127], v[128:131], v[186:189], v[124:127]
	v_mfma_f32_16x16x32_bf16 v[120:123], v[136:139], v[186:189], v[120:123]
	v_mfma_f32_16x16x32_bf16 v[116:119], v[128:131], v[194:197], v[116:119]
	v_mfma_f32_16x16x32_bf16 v[112:115], v[136:139], v[194:197], v[112:115]
	v_mfma_f32_16x16x32_bf16 v[92:95], v[128:131], v[202:205], v[92:95]
	v_mfma_f32_16x16x32_bf16 v[88:91], v[136:139], v[202:205], v[88:91]
	v_mfma_f32_16x16x32_bf16 v[84:87], v[128:131], v[210:213], v[84:87]
	v_mfma_f32_16x16x32_bf16 v[80:83], v[136:139], v[210:213], v[80:83]
	v_mfma_f32_16x16x32_bf16 v[124:127], v[132:135], v[190:193], v[124:127]
	v_mfma_f32_16x16x32_bf16 v[120:123], v[140:143], v[190:193], v[120:123]
	v_mfma_f32_16x16x32_bf16 v[116:119], v[132:135], v[198:201], v[116:119]
	v_mfma_f32_16x16x32_bf16 v[112:115], v[140:143], v[198:201], v[112:115]
	v_mfma_f32_16x16x32_bf16 v[92:95], v[132:135], v[206:209], v[92:95]
	v_mfma_f32_16x16x32_bf16 v[88:91], v[140:143], v[206:209], v[88:91]
	v_mfma_f32_16x16x32_bf16 v[84:87], v[132:135], v[214:217], v[84:87]
	v_mfma_f32_16x16x32_bf16 v[80:83], v[140:143], v[214:217], v[80:83]
	v_mfma_f32_16x16x32_bf16 v[108:111], v[160:163], v[186:189], v[108:111]
	v_mfma_f32_16x16x32_bf16 v[104:107], v[178:181], v[186:189], v[104:107]
	v_mfma_f32_16x16x32_bf16 v[100:103], v[160:163], v[194:197], v[100:103]
	v_mfma_f32_16x16x32_bf16 v[96:99], v[178:181], v[194:197], v[96:99]
	v_mfma_f32_16x16x32_bf16 v[76:79], v[160:163], v[202:205], v[76:79]
	v_mfma_f32_16x16x32_bf16 v[72:75], v[178:181], v[202:205], v[72:75]
	v_mfma_f32_16x16x32_bf16 v[68:71], v[160:163], v[210:213], v[68:71]
	v_mfma_f32_16x16x32_bf16 v[64:67], v[178:181], v[210:213], v[64:67]
	v_mfma_f32_16x16x32_bf16 v[108:111], v[174:177], v[190:193], v[108:111]
	v_mfma_f32_16x16x32_bf16 v[104:107], v[182:185], v[190:193], v[104:107]
	v_mfma_f32_16x16x32_bf16 v[100:103], v[174:177], v[198:201], v[100:103]
	v_mfma_f32_16x16x32_bf16 v[96:99], v[182:185], v[198:201], v[96:99]
	v_mfma_f32_16x16x32_bf16 v[76:79], v[174:177], v[206:209], v[76:79]
	v_mfma_f32_16x16x32_bf16 v[72:75], v[182:185], v[206:209], v[72:75]
	v_mfma_f32_16x16x32_bf16 v[68:71], v[174:177], v[214:217], v[68:71]
	v_mfma_f32_16x16x32_bf16 v[64:67], v[182:185], v[214:217], v[64:67]
	s_setprio 0
	s_barrier
	s_add_i32 s56, s47, s39
	v_lshl_add_u64 v[164:165], s[28:29], 0, v[148:149]
	s_mov_b32 m0, s56
	ds_read_b128 v[186:189], v173 offset:16384
	ds_read_b128 v[190:193], v173 offset:17408
	ds_read_b128 v[194:197], v173 offset:18432
	ds_read_b128 v[198:201], v173 offset:19456
	ds_read_b128 v[202:205], v173 offset:20480
	ds_read_b128 v[206:209], v173 offset:21504
	ds_read_b128 v[210:213], v173 offset:22528
	ds_read_b128 v[214:217], v173 offset:23552
	global_load_lds_dwordx4 v[164:165], off
	s_add_i32 m0, s56, 0x2000
	s_add_u32 s56, s28, 0x100000
	v_lshl_add_u64 v[218:219], s[28:29], 0, v[144:145]
	s_addc_u32 s57, s29, 0
	s_add_i32 s58, s48, s39
	global_load_lds_dwordx4 v[218:219], off
	v_lshl_add_u64 v[220:221], s[56:57], 0, v[148:149]
	s_mov_b32 m0, s58
	v_lshl_add_u64 v[222:223], s[30:31], 0, v[146:147]
	global_load_lds_dwordx4 v[220:221], off
	v_lshl_add_u64 v[220:221], s[56:57], 0, v[144:145]
	s_add_i32 m0, s58, 0x2000
	s_nop 0
	global_load_lds_dwordx4 v[220:221], off
	v_lshl_add_u64 v[220:221], s[30:31], 0, v[150:151]
	s_mov_b32 m0, s25
	s_nop 0
	global_load_lds_dwordx4 v[220:221], off
	s_mov_b32 m0, s40
	s_nop 0
	global_load_lds_dwordx4 v[222:223], off
	s_waitcnt vmcnt(8)
	s_waitcnt lgkmcnt(0)
	s_barrier
; #define PG8_STAGE(bufoff, gbase, voff) do { _Pragma("unroll") for (int _i = 0; _i < 2; ++_i) \
;         __builtin_amdgcn_global_load_lds((const unsigned*)((const char*)(gbase) + (voff)[_i]), (PG8_LAS unsigned*)(lds + (bufoff) + ldsw + _i * 8192), 16, 0, 0); } while (0)
; #define PG8_LDA(dst, b, h) do { _Pragma("unroll") for (int m = 0; m < 4; ++m) _Pragma("unroll") for (int k = 0; k < 2; ++k) dst[m][k] = *(const PG8_LAS bf16x8*)(lds + PG8_SA(b, h) + aoff + m * 2048 + k * 1024); } while (0)
; #define PG8_LDB(dst, b, h) do { _Pragma("unroll") for (int n = 0; n < 2; ++n) _Pragma("unroll") for (int k = 0; k < 2; ++k) dst[n][k] = *(const PG8_LAS bf16x8*)(lds + PG8_SB(b, h) + boff + n * 2048 + k * 1024); } while (0)
; #define PG8_MMA(ai, bj, At, Bt) do { __builtin_amdgcn_s_setprio(1); _Pragma("unroll") for (int m = 0; m < 4; ++m) _Pragma("unroll") for (int n = 0; n < 2; ++n) _Pragma("unroll") for (int k = 0; k < 2; ++k) \
;         acc[ai][bj][m][n] = __builtin_amdgcn_mfma_f32_16x16x32_bf16(Bt[n][k], At[m][k], acc[ai][bj][m][n], 0, 0, 0); __builtin_amdgcn_s_setprio(0); } while (0)
; #define PG8_WAIT_V(n) asm volatile("s_waitcnt vmcnt(" #n ")" ::: "memory")
; #define PG8_WAIT_L(n) asm volatile("s_waitcnt lgkmcnt(" #n ")" ::: "memory")
; #define PG8_BAR __builtin_amdgcn_s_barrier()
; #define PG8_SCHED __builtin_amdgcn_sched_barrier(0)
; template <class Epi, class Sched, bool ALIGN_EPI = false, bool SP2 = false>
; __device__ __forceinline__ void gemm_phase(PG8_LAS unsigned char* lds, const Gemm g, const Sched& S, const Epi& E, const int tid_in) {
;     ...
;             PG8_WAIT_V(8); PG8_WAIT_L(0); PG8_BAR; PG8_MMA(1, 0, At, B0); PG8_MMA(1, 1, At, B1); PG8_BAR; PG8_SCHED;
;             PG8_LDB(B0, 1, 0); PG8_LDB(B1, 1, 1); PG8_SCHED; PG8_LDA(At, 1, 0); PG8_STAGE(PG8_SA(0, 1), a2 + hstep, voffA);
;             PG8_WAIT_V(8); PG8_WAIT_L(0); PG8_BAR; PG8_MMA(0, 0, At, B0); PG8_MMA(0, 1, At, B1); PG8_BAR; PG8_SCHED;
	s_setprio 1
	v_mfma_f32_16x16x32_bf16 v[60:63], v[128:131], v[186:189], v[60:63]
	v_mfma_f32_16x16x32_bf16 v[56:59], v[136:139], v[186:189], v[56:59]
	v_mfma_f32_16x16x32_bf16 v[52:55], v[128:131], v[194:197], v[52:55]
	v_mfma_f32_16x16x32_bf16 v[48:51], v[136:139], v[194:197], v[48:51]
	v_mfma_f32_16x16x32_bf16 v[28:31], v[128:131], v[202:205], v[28:31]
	v_mfma_f32_16x16x32_bf16 v[24:27], v[136:139], v[202:205], v[24:27]
	v_mfma_f32_16x16x32_bf16 v[20:23], v[128:131], v[210:213], v[20:23]
	v_mfma_f32_16x16x32_bf16 v[16:19], v[136:139], v[210:213], v[16:19]
	v_mfma_f32_16x16x32_bf16 v[60:63], v[132:135], v[190:193], v[60:63]
	v_mfma_f32_16x16x32_bf16 v[56:59], v[140:143], v[190:193], v[56:59]
	v_mfma_f32_16x16x32_bf16 v[52:55], v[132:135], v[198:201], v[52:55]
	v_mfma_f32_16x16x32_bf16 v[48:51], v[140:143], v[198:201], v[48:51]
	v_mfma_f32_16x16x32_bf16 v[28:31], v[132:135], v[206:209], v[28:31]
	v_mfma_f32_16x16x32_bf16 v[24:27], v[140:143], v[206:209], v[24:27]
	v_mfma_f32_16x16x32_bf16 v[20:23], v[132:135], v[214:217], v[20:23]
	v_mfma_f32_16x16x32_bf16 v[16:19], v[140:143], v[214:217], v[16:19]
	v_mfma_f32_16x16x32_bf16 v[44:47], v[160:163], v[186:189], v[44:47]
	v_mfma_f32_16x16x32_bf16 v[40:43], v[178:181], v[186:189], v[40:43]
	v_mfma_f32_16x16x32_bf16 v[36:39], v[160:163], v[194:197], v[36:39]
	v_mfma_f32_16x16x32_bf16 v[32:35], v[178:181], v[194:197], v[32:35]
	v_mfma_f32_16x16x32_bf16 v[12:15], v[160:163], v[202:205], v[12:15]
	v_mfma_f32_16x16x32_bf16 v[8:11], v[178:181], v[202:205], v[8:11]
	v_mfma_f32_16x16x32_bf16 v[4:7], v[160:163], v[210:213], v[4:7]
	v_mfma_f32_16x16x32_bf16 v[0:3], v[178:181], v[210:213], v[0:3]
	v_mfma_f32_16x16x32_bf16 v[44:47], v[174:177], v[190:193], v[44:47]
	v_mfma_f32_16x16x32_bf16 v[40:43], v[182:185], v[190:193], v[40:43]
	v_mfma_f32_16x16x32_bf16 v[36:39], v[174:177], v[198:201], v[36:39]
	v_mfma_f32_16x16x32_bf16 v[32:35], v[182:185], v[198:201], v[32:35]
	v_mfma_f32_16x16x32_bf16 v[12:15], v[174:177], v[206:209], v[12:15]
	v_mfma_f32_16x16x32_bf16 v[8:11], v[182:185], v[206:209], v[8:11]
	v_mfma_f32_16x16x32_bf16 v[4:7], v[174:177], v[214:217], v[4:7]
	v_mfma_f32_16x16x32_bf16 v[0:3], v[182:185], v[214:217], v[0:3]
	s_setprio 0
	s_barrier
	s_add_i32 s56, 0, 0x18000
	s_add_i32 s57, 0, 0x1c000
	v_add_u32_e32 v140, s56, v169
	v_add_u32_e32 v182, s57, v169
	ds_read_b128 v[128:131], v140
	ds_read_b128 v[132:135], v140 offset:1024
	ds_read_b128 v[136:139], v140 offset:2048
	ds_read_b128 v[140:143], v140 offset:3072
	ds_read_b128 v[160:163], v182
	ds_read_b128 v[174:177], v182 offset:1024
	ds_read_b128 v[178:181], v182 offset:2048
	ds_read_b128 v[182:185], v182 offset:3072
	s_add_u32 s30, s30, 0x100000
	s_addc_u32 s31, s31, 0
	s_mov_b32 m0, s41
	v_lshl_add_u64 v[224:225], s[30:31], 0, v[150:151]
	ds_read_b128 v[186:189], v173 offset:32768
	ds_read_b128 v[190:193], v173 offset:33792
	ds_read_b128 v[194:197], v173 offset:34816
	ds_read_b128 v[198:201], v173 offset:35840
	ds_read_b128 v[202:205], v173 offset:36864
	ds_read_b128 v[206:209], v173 offset:37888
	ds_read_b128 v[210:213], v173 offset:38912
	ds_read_b128 v[214:217], v173 offset:39936
	global_load_lds_dwordx4 v[224:225], off
	v_lshl_add_u64 v[224:225], s[30:31], 0, v[146:147]
	s_mov_b32 m0, s42
	s_nop 0
	global_load_lds_dwordx4 v[224:225], off
	s_waitcnt vmcnt(8)
	s_waitcnt lgkmcnt(0)
	s_barrier
	s_setprio 1
	v_mfma_f32_16x16x32_bf16 v[124:127], v[128:131], v[186:189], v[124:127]
	v_mfma_f32_16x16x32_bf16 v[120:123], v[136:139], v[186:189], v[120:123]
	v_mfma_f32_16x16x32_bf16 v[116:119], v[128:131], v[194:197], v[116:119]
	v_mfma_f32_16x16x32_bf16 v[112:115], v[136:139], v[194:197], v[112:115]
	v_mfma_f32_16x16x32_bf16 v[92:95], v[128:131], v[202:205], v[92:95]
	v_mfma_f32_16x16x32_bf16 v[88:91], v[136:139], v[202:205], v[88:91]
	v_mfma_f32_16x16x32_bf16 v[84:87], v[128:131], v[210:213], v[84:87]
	v_mfma_f32_16x16x32_bf16 v[80:83], v[136:139], v[210:213], v[80:83]
	v_mfma_f32_16x16x32_bf16 v[124:127], v[132:135], v[190:193], v[124:127]
	v_mfma_f32_16x16x32_bf16 v[120:123], v[140:143], v[190:193], v[120:123]
	v_mfma_f32_16x16x32_bf16 v[116:119], v[132:135], v[198:201], v[116:119]
	v_mfma_f32_16x16x32_bf16 v[112:115], v[140:143], v[198:201], v[112:115]
	v_mfma_f32_16x16x32_bf16 v[92:95], v[132:135], v[206:209], v[92:95]
	v_mfma_f32_16x16x32_bf16 v[88:91], v[140:143], v[206:209], v[88:91]
	v_mfma_f32_16x16x32_bf16 v[84:87], v[132:135], v[214:217], v[84:87]
	v_mfma_f32_16x16x32_bf16 v[80:83], v[140:143], v[214:217], v[80:83]
	v_mfma_f32_16x16x32_bf16 v[108:111], v[160:163], v[186:189], v[108:111]
	v_mfma_f32_16x16x32_bf16 v[104:107], v[178:181], v[186:189], v[104:107]
	v_mfma_f32_16x16x32_bf16 v[100:103], v[160:163], v[194:197], v[100:103]
	v_mfma_f32_16x16x32_bf16 v[96:99], v[178:181], v[194:197], v[96:99]
	v_mfma_f32_16x16x32_bf16 v[76:79], v[160:163], v[202:205], v[76:79]
	v_mfma_f32_16x16x32_bf16 v[72:75], v[178:181], v[202:205], v[72:75]
	v_mfma_f32_16x16x32_bf16 v[68:71], v[160:163], v[210:213], v[68:71]
	v_mfma_f32_16x16x32_bf16 v[64:67], v[178:181], v[210:213], v[64:67]
	v_mfma_f32_16x16x32_bf16 v[108:111], v[174:177], v[190:193], v[108:111]
	v_mfma_f32_16x16x32_bf16 v[104:107], v[182:185], v[190:193], v[104:107]
	v_mfma_f32_16x16x32_bf16 v[100:103], v[174:177], v[198:201], v[100:103]
	v_mfma_f32_16x16x32_bf16 v[96:99], v[182:185], v[198:201], v[96:99]
	v_mfma_f32_16x16x32_bf16 v[76:79], v[174:177], v[206:209], v[76:79]
	v_mfma_f32_16x16x32_bf16 v[72:75], v[182:185], v[206:209], v[72:75]
	v_mfma_f32_16x16x32_bf16 v[68:71], v[174:177], v[214:217], v[68:71]
	v_mfma_f32_16x16x32_bf16 v[64:67], v[182:185], v[214:217], v[64:67]
	s_setprio 0
	s_barrier
; #define PG8_STAGE(bufoff, gbase, voff) do { _Pragma("unroll") for (int _i = 0; _i < 2; ++_i) \
;         __builtin_amdgcn_global_load_lds((const unsigned*)((const char*)(gbase) + (voff)[_i]), (PG8_LAS unsigned*)(lds + (bufoff) + ldsw + _i * 8192), 16, 0, 0); } while (0)
; #define PG8_LDA(dst, b, h) do { _Pragma("unroll") for (int m = 0; m < 4; ++m) _Pragma("unroll") for (int k = 0; k < 2; ++k) dst[m][k] = *(const PG8_LAS bf16x8*)(lds + PG8_SA(b, h) + aoff + m * 2048 + k * 1024); } while (0)
; #define PG8_MMA(ai, bj, At, Bt) do { __builtin_amdgcn_s_setprio(1); _Pragma("unroll") for (int m = 0; m < 4; ++m) _Pragma("unroll") for (int n = 0; n < 2; ++n) _Pragma("unroll") for (int k = 0; k < 2; ++k) \
;         acc[ai][bj][m][n] = __builtin_amdgcn_mfma_f32_16x16x32_bf16(Bt[n][k], At[m][k], acc[ai][bj][m][n], 0, 0, 0); __builtin_amdgcn_s_setprio(0); } while (0)
; #define PG8_WAIT_V(n) asm volatile("s_waitcnt vmcnt(" #n ")" ::: "memory")
; #define PG8_WAIT_L(n) asm volatile("s_waitcnt lgkmcnt(" #n ")" ::: "memory")
; #define PG8_BAR __builtin_amdgcn_s_barrier()
; #define PG8_SCHED __builtin_amdgcn_sched_barrier(0)
; template <class Epi, class Sched, bool ALIGN_EPI = false, bool SP2 = false>
; __device__ __forceinline__ void gemm_phase(PG8_LAS unsigned char* lds, const Gemm g, const Sched& S, const Epi& E, const int tid_in) {
;     ...
;             PG8_LDA(At, 1, 1); PG8_STAGE(PG8_SB(1, 0), b3, voffB); PG8_STAGE(PG8_SB(1, 1), b3 + hstep, voffB); PG8_STAGE(PG8_SA(1, 0), a3, voffA);
;             PG8_WAIT_V(8); PG8_WAIT_L(0); PG8_BAR; PG8_MMA(1, 0, At, B0); PG8_MMA(1, 1, At, B1); PG8_BAR; PG8_SCHED;
	s_add_i32 s30, s56, s39
	v_lshl_add_u64 v[164:165], v[164:165], 0, s[8:9]
	s_mov_b32 m0, s30
	ds_read_b128 v[186:189], v173 offset:49152
	ds_read_b128 v[190:193], v173 offset:50176
	ds_read_b128 v[194:197], v173 offset:51200
	ds_read_b128 v[198:201], v173 offset:52224
	ds_read_b128 v[202:205], v173 offset:53248
	ds_read_b128 v[206:209], v173 offset:54272
	ds_read_b128 v[210:213], v173 offset:55296
	ds_read_b128 v[214:217], v173 offset:56320
	global_load_lds_dwordx4 v[164:165], off
	s_add_i32 m0, s30, 0x2000
	s_add_u32 s28, s28, 0x100080
	v_lshl_add_u64 v[164:165], v[218:219], 0, s[8:9]
	s_addc_u32 s29, s29, 0
	s_add_i32 s30, s57, s39
	global_load_lds_dwordx4 v[164:165], off
	v_lshl_add_u64 v[164:165], s[28:29], 0, v[148:149]
	s_mov_b32 m0, s30
	s_nop 0
	global_load_lds_dwordx4 v[164:165], off
	v_lshl_add_u64 v[164:165], s[28:29], 0, v[144:145]
	s_add_i32 m0, s30, 0x2000
	s_nop 0
	global_load_lds_dwordx4 v[164:165], off
	v_lshl_add_u64 v[164:165], v[220:221], 0, s[8:9]
	s_mov_b32 m0, s45
	s_nop 0
	global_load_lds_dwordx4 v[164:165], off
	v_lshl_add_u64 v[164:165], v[222:223], 0, s[8:9]
	s_mov_b32 m0, s46
	s_nop 0
	global_load_lds_dwordx4 v[164:165], off
	s_waitcnt vmcnt(8)
	s_waitcnt lgkmcnt(0)
	s_barrier
	s_setprio 1
	v_mfma_f32_16x16x32_bf16 v[60:63], v[128:131], v[186:189], v[60:63]
	v_mfma_f32_16x16x32_bf16 v[56:59], v[136:139], v[186:189], v[56:59]
	v_mfma_f32_16x16x32_bf16 v[52:55], v[128:131], v[194:197], v[52:55]
	v_mfma_f32_16x16x32_bf16 v[48:51], v[136:139], v[194:197], v[48:51]
	v_mfma_f32_16x16x32_bf16 v[28:31], v[128:131], v[202:205], v[28:31]
	v_mfma_f32_16x16x32_bf16 v[24:27], v[136:139], v[202:205], v[24:27]
	v_mfma_f32_16x16x32_bf16 v[20:23], v[128:131], v[210:213], v[20:23]
	v_mfma_f32_16x16x32_bf16 v[16:19], v[136:139], v[210:213], v[16:19]
	v_mfma_f32_16x16x32_bf16 v[60:63], v[132:135], v[190:193], v[60:63]
	v_mfma_f32_16x16x32_bf16 v[56:59], v[140:143], v[190:193], v[56:59]
	v_mfma_f32_16x16x32_bf16 v[52:55], v[132:135], v[198:201], v[52:55]
	v_mfma_f32_16x16x32_bf16 v[48:51], v[140:143], v[198:201], v[48:51]
	v_mfma_f32_16x16x32_bf16 v[28:31], v[132:135], v[206:209], v[28:31]
	v_mfma_f32_16x16x32_bf16 v[24:27], v[140:143], v[206:209], v[24:27]
	v_mfma_f32_16x16x32_bf16 v[20:23], v[132:135], v[214:217], v[20:23]
	v_mfma_f32_16x16x32_bf16 v[16:19], v[140:143], v[214:217], v[16:19]
	v_mfma_f32_16x16x32_bf16 v[44:47], v[160:163], v[186:189], v[44:47]
	v_mfma_f32_16x16x32_bf16 v[40:43], v[178:181], v[186:189], v[40:43]
	v_mfma_f32_16x16x32_bf16 v[36:39], v[160:163], v[194:197], v[36:39]
	v_mfma_f32_16x16x32_bf16 v[32:35], v[178:181], v[194:197], v[32:35]
	v_mfma_f32_16x16x32_bf16 v[12:15], v[160:163], v[202:205], v[12:15]
	v_mfma_f32_16x16x32_bf16 v[8:11], v[178:181], v[202:205], v[8:11]
	v_mfma_f32_16x16x32_bf16 v[4:7], v[160:163], v[210:213], v[4:7]
	v_mfma_f32_16x16x32_bf16 v[0:3], v[178:181], v[210:213], v[0:3]
	v_mfma_f32_16x16x32_bf16 v[44:47], v[174:177], v[190:193], v[44:47]
	v_mfma_f32_16x16x32_bf16 v[40:43], v[182:185], v[190:193], v[40:43]
	v_mfma_f32_16x16x32_bf16 v[36:39], v[174:177], v[198:201], v[36:39]
	v_mfma_f32_16x16x32_bf16 v[32:35], v[182:185], v[198:201], v[32:35]
	v_mfma_f32_16x16x32_bf16 v[12:15], v[174:177], v[206:209], v[12:15]
	v_mfma_f32_16x16x32_bf16 v[8:11], v[182:185], v[206:209], v[8:11]
	v_mfma_f32_16x16x32_bf16 v[4:7], v[174:177], v[214:217], v[4:7]
	v_mfma_f32_16x16x32_bf16 v[0:3], v[182:185], v[214:217], v[0:3]
	s_setprio 0
	s_barrier
	s_add_i32 s55, s55, 2
	s_add_u32 s26, s26, 0x100
	s_addc_u32 s27, s27, 0
	s_add_u32 s53, s53, 0x100
	s_addc_u32 s54, s54, 0
	s_cmp_gt_u32 s55, 61
	s_cbranch_scc0 .LBB0_1613
	s_and_b64 vcc, exec, s[10:11]
	s_cbranch_vccz .LBB0_1616
	s_barrier

; #define PG8_STAGE(bufoff, gbase, voff) do { _Pragma("unroll") for (int _i = 0; _i < 2; ++_i) \
;         __builtin_amdgcn_global_load_lds((const unsigned*)((const char*)(gbase) + (voff)[_i]), (PG8_LAS unsigned*)(lds + (bufoff) + ldsw + _i * 8192), 16, 0, 0); } while (0)
; #define PG8_LDA(dst, b, h) do { _Pragma("unroll") for (int m = 0; m < 4; ++m) _Pragma("unroll") for (int k = 0; k < 2; ++k) dst[m][k] = *(const PG8_LAS bf16x8*)(lds + PG8_SA(b, h) + aoff + m * 2048 + k * 1024); } while (0)
; #define PG8_LDB(dst, b, h) do { _Pragma("unroll") for (int n = 0; n < 2; ++n) _Pragma("unroll") for (int k = 0; k < 2; ++k) dst[n][k] = *(const PG8_LAS bf16x8*)(lds + PG8_SB(b, h) + boff + n * 2048 + k * 1024); } while (0)
; #define PG8_MMA(ai, bj, At, Bt) do { __builtin_amdgcn_s_setprio(1); _Pragma("unroll") for (int m = 0; m < 4; ++m) _Pragma("unroll") for (int n = 0; n < 2; ++n) _Pragma("unroll") for (int k = 0; k < 2; ++k) \
;         acc[ai][bj][m][n] = __builtin_amdgcn_mfma_f32_16x16x32_bf16(Bt[n][k], At[m][k], acc[ai][bj][m][n], 0, 0, 0); __builtin_amdgcn_s_setprio(0); } while (0)
; #define PG8_WAIT_V(n) asm volatile("s_waitcnt vmcnt(" #n ")" ::: "memory")
; #define PG8_WAIT_L(n) asm volatile("s_waitcnt lgkmcnt(" #n ")" ::: "memory")
; #define PG8_BAR __builtin_amdgcn_s_barrier()
; template <class Epi, class Sched, bool ALIGN_EPI = false, bool SP2 = false>
; __device__ __forceinline__ void gemm_phase(PG8_LAS unsigned char* lds, const Gemm g, const Sched& S, const Epi& E, const int tid_in) {
;     ...
;             const char* a1 = cA + (size_t)(t + 1) * kstep;
;             const char* a2 = last ? nA : cA + (size_t)(t + 2) * kstep; const char* b2 = last ? nB : cB + (size_t)(t + 2) * kstep;
;             const char* a3 = a2 + kstep; const char* b3 = b2 + kstep;
;             if (last && has_next) S.a_ready(nxt);
;             if constexpr (SP2) {
;             PG8_LDB(B0, 0, 0); PG8_LDB(B1, 0, 1); PG8_SCHED; PG8_LDA(At, 0, 0); PG8_STAGE(PG8_SA(1, 1), a1 + hstep, voffA);
;             PG8_WAIT_V(8); PG8_WAIT_L(0); PG8_BAR; PG8_MMA(0, 0, At, B0); PG8_MMA(0, 1, At, B1); PG8_BAR; PG8_SCHED;
;             PG8_LDA(At, 0, 1); PG8_STAGE(PG8_SB(0, 0), b2, voffB); PG8_STAGE(PG8_SB(0, 1), b2 + hstep, voffB); PG8_STAGE(PG8_SA(0, 0), a2, voffA);
;             PG8_WAIT_V(8); PG8_WAIT_L(0); PG8_BAR; PG8_MMA(1, 0, At, B0); PG8_MMA(1, 1, At, B1); PG8_BAR; PG8_SCHED;
.LBB0_1759:
	ds_read_b128 v[152:155], v181
	ds_read_b128 v[156:159], v181 offset:1024
	ds_read_b128 v[160:163], v181 offset:2048
	ds_read_b128 v[164:167], v181 offset:3072
	ds_read_b128 v[168:171], v182
	ds_read_b128 v[172:175], v182 offset:1024
	ds_read_b128 v[176:179], v182 offset:2048
	ds_read_b128 v[184:187], v182 offset:3072
	s_add_u32 s14, s12, 0xfff00080
	s_addc_u32 s15, s13, -1
	s_cmp_eq_u32 s20, 60
	s_cselect_b32 s17, s1, s15
	s_cselect_b32 s16, s4, s14
	s_cselect_b32 s15, s5, s11
	s_cselect_b32 s14, s6, s7
	v_lshl_add_u64 v[220:221], s[12:13], 0, v[144:145]
	s_add_i32 m0, s52, 0xc000
	ds_read_b128 v[188:191], v183
	ds_read_b128 v[192:195], v183 offset:1024
	ds_read_b128 v[196:199], v183 offset:2048
	ds_read_b128 v[200:203], v183 offset:3072
	ds_read_b128 v[204:207], v183 offset:4096
	ds_read_b128 v[208:211], v183 offset:5120
	ds_read_b128 v[212:215], v183 offset:6144
	ds_read_b128 v[216:219], v183 offset:7168
	global_load_lds_dwordx4 v[220:221], off
	v_lshl_add_u64 v[220:221], s[12:13], 0, v[146:147]
	s_add_i32 m0, s52, 0xe000
	s_nop 0
	global_load_lds_dwordx4 v[220:221], off
	s_waitcnt vmcnt(8)
	s_waitcnt lgkmcnt(0)
	s_barrier
	s_setprio 1
	v_mfma_f32_16x16x32_bf16 v[124:127], v[152:155], v[188:191], v[124:127]
	v_mfma_f32_16x16x32_bf16 v[120:123], v[160:163], v[188:191], v[120:123]
	v_mfma_f32_16x16x32_bf16 v[108:111], v[152:155], v[196:199], v[108:111]
	v_mfma_f32_16x16x32_bf16 v[104:107], v[160:163], v[196:199], v[104:107]
	v_mfma_f32_16x16x32_bf16 v[92:95], v[152:155], v[204:207], v[92:95]
	v_mfma_f32_16x16x32_bf16 v[88:91], v[160:163], v[204:207], v[88:91]
	v_mfma_f32_16x16x32_bf16 v[76:79], v[152:155], v[212:215], v[76:79]
	v_mfma_f32_16x16x32_bf16 v[72:75], v[160:163], v[212:215], v[72:75]
	v_mfma_f32_16x16x32_bf16 v[124:127], v[156:159], v[192:195], v[124:127]
	v_mfma_f32_16x16x32_bf16 v[120:123], v[164:167], v[192:195], v[120:123]
	v_mfma_f32_16x16x32_bf16 v[108:111], v[156:159], v[200:203], v[108:111]
	v_mfma_f32_16x16x32_bf16 v[104:107], v[164:167], v[200:203], v[104:107]
	v_mfma_f32_16x16x32_bf16 v[92:95], v[156:159], v[208:211], v[92:95]
	v_mfma_f32_16x16x32_bf16 v[88:91], v[164:167], v[208:211], v[88:91]
	v_mfma_f32_16x16x32_bf16 v[76:79], v[156:159], v[216:219], v[76:79]
	v_mfma_f32_16x16x32_bf16 v[72:75], v[164:167], v[216:219], v[72:75]
	v_mfma_f32_16x16x32_bf16 v[116:119], v[168:171], v[188:191], v[116:119]
	v_mfma_f32_16x16x32_bf16 v[112:115], v[176:179], v[188:191], v[112:115]
	v_mfma_f32_16x16x32_bf16 v[100:103], v[168:171], v[196:199], v[100:103]
	v_mfma_f32_16x16x32_bf16 v[96:99], v[176:179], v[196:199], v[96:99]
	v_mfma_f32_16x16x32_bf16 v[84:87], v[168:171], v[204:207], v[84:87]
	v_mfma_f32_16x16x32_bf16 v[80:83], v[176:179], v[204:207], v[80:83]
	v_mfma_f32_16x16x32_bf16 v[68:71], v[168:171], v[212:215], v[68:71]
	v_mfma_f32_16x16x32_bf16 v[64:67], v[176:179], v[212:215], v[64:67]
	v_mfma_f32_16x16x32_bf16 v[116:119], v[172:175], v[192:195], v[116:119]
	v_mfma_f32_16x16x32_bf16 v[112:115], v[184:187], v[192:195], v[112:115]
	v_mfma_f32_16x16x32_bf16 v[100:103], v[172:175], v[200:203], v[100:103]
	v_mfma_f32_16x16x32_bf16 v[96:99], v[184:187], v[200:203], v[96:99]
	v_mfma_f32_16x16x32_bf16 v[84:87], v[172:175], v[208:211], v[84:87]
	v_mfma_f32_16x16x32_bf16 v[80:83], v[184:187], v[208:211], v[80:83]
	v_mfma_f32_16x16x32_bf16 v[68:71], v[172:175], v[216:219], v[68:71]
	v_mfma_f32_16x16x32_bf16 v[64:67], v[184:187], v[216:219], v[64:67]
	s_setprio 0
	s_barrier
	s_add_i32 s21, s34, s37
	v_lshl_add_u64 v[220:221], s[14:15], 0, v[130:131]
	s_mov_b32 m0, s21
	ds_read_b128 v[188:191], v183 offset:16384
	ds_read_b128 v[192:195], v183 offset:17408
	ds_read_b128 v[196:199], v183 offset:18432
	ds_read_b128 v[200:203], v183 offset:19456
	ds_read_b128 v[204:207], v183 offset:20480
	ds_read_b128 v[208:211], v183 offset:21504
	ds_read_b128 v[212:215], v183 offset:22528
	ds_read_b128 v[216:219], v183 offset:23552
	global_load_lds_dwordx4 v[220:221], off
	s_add_i32 m0, s21, 0x2000
	s_add_u32 s22, s14, 0x100000
	v_lshl_add_u64 v[222:223], s[14:15], 0, v[134:135]
	s_addc_u32 s23, s15, 0
	s_add_i32 s21, s3, s37
	global_load_lds_dwordx4 v[222:223], off
	v_lshl_add_u64 v[224:225], s[22:23], 0, v[130:131]
	s_mov_b32 m0, s21
	v_lshl_add_u64 v[226:227], s[16:17], 0, v[132:133]
	global_load_lds_dwordx4 v[224:225], off
	v_lshl_add_u64 v[224:225], s[22:23], 0, v[134:135]
	s_add_i32 m0, s21, 0x2000
	s_nop 0
	global_load_lds_dwordx4 v[224:225], off
	v_lshl_add_u64 v[224:225], s[16:17], 0, v[128:129]
	s_mov_b32 m0, s52
	s_nop 0
	global_load_lds_dwordx4 v[224:225], off
	s_mov_b32 m0, s53
	s_nop 0
	global_load_lds_dwordx4 v[226:227], off
	s_waitcnt vmcnt(8)
	s_waitcnt lgkmcnt(0)
	s_barrier
; #define PG8_STAGE(bufoff, gbase, voff) do { _Pragma("unroll") for (int _i = 0; _i < 2; ++_i) \
;         __builtin_amdgcn_global_load_lds((const unsigned*)((const char*)(gbase) + (voff)[_i]), (PG8_LAS unsigned*)(lds + (bufoff) + ldsw + _i * 8192), 16, 0, 0); } while (0)
; #define PG8_LDA(dst, b, h) do { _Pragma("unroll") for (int m = 0; m < 4; ++m) _Pragma("unroll") for (int k = 0; k < 2; ++k) dst[m][k] = *(const PG8_LAS bf16x8*)(lds + PG8_SA(b, h) + aoff + m * 2048 + k * 1024); } while (0)
; #define PG8_LDB(dst, b, h) do { _Pragma("unroll") for (int n = 0; n < 2; ++n) _Pragma("unroll") for (int k = 0; k < 2; ++k) dst[n][k] = *(const PG8_LAS bf16x8*)(lds + PG8_SB(b, h) + boff + n * 2048 + k * 1024); } while (0)
; #define PG8_MMA(ai, bj, At, Bt) do { __builtin_amdgcn_s_setprio(1); _Pragma("unroll") for (int m = 0; m < 4; ++m) _Pragma("unroll") for (int n = 0; n < 2; ++n) _Pragma("unroll") for (int k = 0; k < 2; ++k) \
;         acc[ai][bj][m][n] = __builtin_amdgcn_mfma_f32_16x16x32_bf16(Bt[n][k], At[m][k], acc[ai][bj][m][n], 0, 0, 0); __builtin_amdgcn_s_setprio(0); } while (0)
; #define PG8_WAIT_V(n) asm volatile("s_waitcnt vmcnt(" #n ")" ::: "memory")
; #define PG8_WAIT_L(n) asm volatile("s_waitcnt lgkmcnt(" #n ")" ::: "memory")
; #define PG8_BAR __builtin_amdgcn_s_barrier()
; #define PG8_SCHED __builtin_amdgcn_sched_barrier(0)
; template <class Epi, class Sched, bool ALIGN_EPI = false, bool SP2 = false>
; __device__ __forceinline__ void gemm_phase(PG8_LAS unsigned char* lds, const Gemm g, const Sched& S, const Epi& E, const int tid_in) {
;     ...
;             PG8_WAIT_V(8); PG8_WAIT_L(0); PG8_BAR; PG8_MMA(1, 0, At, B0); PG8_MMA(1, 1, At, B1); PG8_BAR; PG8_SCHED;
;             PG8_LDB(B0, 1, 0); PG8_LDB(B1, 1, 1); PG8_SCHED; PG8_LDA(At, 1, 0); PG8_STAGE(PG8_SA(0, 1), a2 + hstep, voffA);
;             PG8_WAIT_V(8); PG8_WAIT_L(0); PG8_BAR; PG8_MMA(0, 0, At, B0); PG8_MMA(0, 1, At, B1); PG8_BAR; PG8_SCHED;
	s_setprio 1
	v_mfma_f32_16x16x32_bf16 v[60:63], v[152:155], v[188:191], v[60:63]
	v_mfma_f32_16x16x32_bf16 v[56:59], v[160:163], v[188:191], v[56:59]
	v_mfma_f32_16x16x32_bf16 v[44:47], v[152:155], v[196:199], v[44:47]
	v_mfma_f32_16x16x32_bf16 v[40:43], v[160:163], v[196:199], v[40:43]
	v_mfma_f32_16x16x32_bf16 v[28:31], v[152:155], v[204:207], v[28:31]
	v_mfma_f32_16x16x32_bf16 v[24:27], v[160:163], v[204:207], v[24:27]
	v_mfma_f32_16x16x32_bf16 v[12:15], v[152:155], v[212:215], v[12:15]
	v_mfma_f32_16x16x32_bf16 v[8:11], v[160:163], v[212:215], v[8:11]
	v_mfma_f32_16x16x32_bf16 v[60:63], v[156:159], v[192:195], v[60:63]
	v_mfma_f32_16x16x32_bf16 v[56:59], v[164:167], v[192:195], v[56:59]
	v_mfma_f32_16x16x32_bf16 v[44:47], v[156:159], v[200:203], v[44:47]
	v_mfma_f32_16x16x32_bf16 v[40:43], v[164:167], v[200:203], v[40:43]
	v_mfma_f32_16x16x32_bf16 v[28:31], v[156:159], v[208:211], v[28:31]
	v_mfma_f32_16x16x32_bf16 v[24:27], v[164:167], v[208:211], v[24:27]
	v_mfma_f32_16x16x32_bf16 v[12:15], v[156:159], v[216:219], v[12:15]
	v_mfma_f32_16x16x32_bf16 v[8:11], v[164:167], v[216:219], v[8:11]
	v_mfma_f32_16x16x32_bf16 v[52:55], v[168:171], v[188:191], v[52:55]
	v_mfma_f32_16x16x32_bf16 v[48:51], v[176:179], v[188:191], v[48:51]
	v_mfma_f32_16x16x32_bf16 v[36:39], v[168:171], v[196:199], v[36:39]
	v_mfma_f32_16x16x32_bf16 v[32:35], v[176:179], v[196:199], v[32:35]
	v_mfma_f32_16x16x32_bf16 v[20:23], v[168:171], v[204:207], v[20:23]
	v_mfma_f32_16x16x32_bf16 v[16:19], v[176:179], v[204:207], v[16:19]
	v_mfma_f32_16x16x32_bf16 v[4:7], v[168:171], v[212:215], v[4:7]
	v_mfma_f32_16x16x32_bf16 v[0:3], v[176:179], v[212:215], v[0:3]
	v_mfma_f32_16x16x32_bf16 v[52:55], v[172:175], v[192:195], v[52:55]
	v_mfma_f32_16x16x32_bf16 v[48:51], v[184:187], v[192:195], v[48:51]
	v_mfma_f32_16x16x32_bf16 v[36:39], v[172:175], v[200:203], v[36:39]
	v_mfma_f32_16x16x32_bf16 v[32:35], v[184:187], v[200:203], v[32:35]
	v_mfma_f32_16x16x32_bf16 v[20:23], v[172:175], v[208:211], v[20:23]
	v_mfma_f32_16x16x32_bf16 v[16:19], v[184:187], v[208:211], v[16:19]
	v_mfma_f32_16x16x32_bf16 v[4:7], v[172:175], v[216:219], v[4:7]
	v_mfma_f32_16x16x32_bf16 v[0:3], v[184:187], v[216:219], v[0:3]
	s_setprio 0
	s_barrier
	s_add_i32 s21, 0, 0x18000
	v_add_u32_e32 v136, s21, v180
	s_add_i32 s22, 0, 0x1c000
	ds_read_b128 v[152:155], v136
	ds_read_b128 v[156:159], v136 offset:1024
	ds_read_b128 v[160:163], v136 offset:2048
	ds_read_b128 v[164:167], v136 offset:3072
	v_add_u32_e32 v136, s22, v180
	ds_read_b128 v[168:171], v136
	ds_read_b128 v[172:175], v136 offset:1024
	ds_read_b128 v[176:179], v136 offset:2048
	ds_read_b128 v[184:187], v136 offset:3072
	s_add_u32 s16, s16, 0x100000
	s_addc_u32 s17, s17, 0
	s_mov_b32 m0, s54
	v_lshl_add_u64 v[228:229], s[16:17], 0, v[128:129]
	ds_read_b128 v[188:191], v183 offset:32768
	ds_read_b128 v[192:195], v183 offset:33792
	ds_read_b128 v[196:199], v183 offset:34816
	ds_read_b128 v[200:203], v183 offset:35840
	ds_read_b128 v[204:207], v183 offset:36864
	ds_read_b128 v[208:211], v183 offset:37888
	ds_read_b128 v[212:215], v183 offset:38912
	ds_read_b128 v[216:219], v183 offset:39936
	global_load_lds_dwordx4 v[228:229], off
	v_lshl_add_u64 v[228:229], s[16:17], 0, v[132:133]
	s_mov_b32 m0, s55
	s_nop 0
	global_load_lds_dwordx4 v[228:229], off
	s_waitcnt vmcnt(8)
	s_waitcnt lgkmcnt(0)
	s_barrier
	s_setprio 1
	v_mfma_f32_16x16x32_bf16 v[124:127], v[152:155], v[188:191], v[124:127]
	v_mfma_f32_16x16x32_bf16 v[120:123], v[160:163], v[188:191], v[120:123]
	v_mfma_f32_16x16x32_bf16 v[108:111], v[152:155], v[196:199], v[108:111]
	v_mfma_f32_16x16x32_bf16 v[104:107], v[160:163], v[196:199], v[104:107]
	v_mfma_f32_16x16x32_bf16 v[92:95], v[152:155], v[204:207], v[92:95]
	v_mfma_f32_16x16x32_bf16 v[88:91], v[160:163], v[204:207], v[88:91]
	v_mfma_f32_16x16x32_bf16 v[76:79], v[152:155], v[212:215], v[76:79]
	v_mfma_f32_16x16x32_bf16 v[72:75], v[160:163], v[212:215], v[72:75]
	v_mfma_f32_16x16x32_bf16 v[124:127], v[156:159], v[192:195], v[124:127]
	v_mfma_f32_16x16x32_bf16 v[120:123], v[164:167], v[192:195], v[120:123]
	v_mfma_f32_16x16x32_bf16 v[108:111], v[156:159], v[200:203], v[108:111]
	v_mfma_f32_16x16x32_bf16 v[104:107], v[164:167], v[200:203], v[104:107]
	v_mfma_f32_16x16x32_bf16 v[92:95], v[156:159], v[208:211], v[92:95]
	v_mfma_f32_16x16x32_bf16 v[88:91], v[164:167], v[208:211], v[88:91]
	v_mfma_f32_16x16x32_bf16 v[76:79], v[156:159], v[216:219], v[76:79]
	v_mfma_f32_16x16x32_bf16 v[72:75], v[164:167], v[216:219], v[72:75]
	v_mfma_f32_16x16x32_bf16 v[116:119], v[168:171], v[188:191], v[116:119]
	v_mfma_f32_16x16x32_bf16 v[112:115], v[176:179], v[188:191], v[112:115]
	v_mfma_f32_16x16x32_bf16 v[100:103], v[168:171], v[196:199], v[100:103]
	v_mfma_f32_16x16x32_bf16 v[96:99], v[176:179], v[196:199], v[96:99]
	v_mfma_f32_16x16x32_bf16 v[84:87], v[168:171], v[204:207], v[84:87]
	v_mfma_f32_16x16x32_bf16 v[80:83], v[176:179], v[204:207], v[80:83]
	v_mfma_f32_16x16x32_bf16 v[68:71], v[168:171], v[212:215], v[68:71]
	v_mfma_f32_16x16x32_bf16 v[64:67], v[176:179], v[212:215], v[64:67]
	v_mfma_f32_16x16x32_bf16 v[116:119], v[172:175], v[192:195], v[116:119]
	v_mfma_f32_16x16x32_bf16 v[112:115], v[184:187], v[192:195], v[112:115]
	v_mfma_f32_16x16x32_bf16 v[100:103], v[172:175], v[200:203], v[100:103]
	v_mfma_f32_16x16x32_bf16 v[96:99], v[184:187], v[200:203], v[96:99]
	v_mfma_f32_16x16x32_bf16 v[84:87], v[172:175], v[208:211], v[84:87]
	v_mfma_f32_16x16x32_bf16 v[80:83], v[184:187], v[208:211], v[80:83]
	v_mfma_f32_16x16x32_bf16 v[68:71], v[172:175], v[216:219], v[68:71]
	v_mfma_f32_16x16x32_bf16 v[64:67], v[184:187], v[216:219], v[64:67]
	s_setprio 0
	s_barrier
; #define PG8_STAGE(bufoff, gbase, voff) do { _Pragma("unroll") for (int _i = 0; _i < 2; ++_i) \
;         __builtin_amdgcn_global_load_lds((const unsigned*)((const char*)(gbase) + (voff)[_i]), (PG8_LAS unsigned*)(lds + (bufoff) + ldsw + _i * 8192), 16, 0, 0); } while (0)
; #define PG8_LDA(dst, b, h) do { _Pragma("unroll") for (int m = 0; m < 4; ++m) _Pragma("unroll") for (int k = 0; k < 2; ++k) dst[m][k] = *(const PG8_LAS bf16x8*)(lds + PG8_SA(b, h) + aoff + m * 2048 + k * 1024); } while (0)
; #define PG8_MMA(ai, bj, At, Bt) do { __builtin_amdgcn_s_setprio(1); _Pragma("unroll") for (int m = 0; m < 4; ++m) _Pragma("unroll") for (int n = 0; n < 2; ++n) _Pragma("unroll") for (int k = 0; k < 2; ++k) \
;         acc[ai][bj][m][n] = __builtin_amdgcn_mfma_f32_16x16x32_bf16(Bt[n][k], At[m][k], acc[ai][bj][m][n], 0, 0, 0); __builtin_amdgcn_s_setprio(0); } while (0)
; #define PG8_WAIT_V(n) asm volatile("s_waitcnt vmcnt(" #n ")" ::: "memory")
; #define PG8_WAIT_L(n) asm volatile("s_waitcnt lgkmcnt(" #n ")" ::: "memory")
; #define PG8_BAR __builtin_amdgcn_s_barrier()
; #define PG8_SCHED __builtin_amdgcn_sched_barrier(0)
; template <class Epi, class Sched, bool ALIGN_EPI = false, bool SP2 = false>
; __device__ __forceinline__ void gemm_phase(PG8_LAS unsigned char* lds, const Gemm g, const Sched& S, const Epi& E, const int tid_in) {
;     ...
;             PG8_LDA(At, 1, 1); PG8_STAGE(PG8_SB(1, 0), b3, voffB); PG8_STAGE(PG8_SB(1, 1), b3 + hstep, voffB); PG8_STAGE(PG8_SA(1, 0), a3, voffA);
;             PG8_WAIT_V(8); PG8_WAIT_L(0); PG8_BAR; PG8_MMA(1, 0, At, B0); PG8_MMA(1, 1, At, B1); PG8_BAR; PG8_SCHED;
	s_add_i32 s16, s21, s37
	v_lshl_add_u64 v[220:221], v[220:221], 0, s[28:29]
	s_mov_b32 m0, s16
	ds_read_b128 v[188:191], v183 offset:49152
	ds_read_b128 v[192:195], v183 offset:50176
	ds_read_b128 v[196:199], v183 offset:51200
	ds_read_b128 v[200:203], v183 offset:52224
	ds_read_b128 v[204:207], v183 offset:53248
	ds_read_b128 v[208:211], v183 offset:54272
	ds_read_b128 v[212:215], v183 offset:55296
	ds_read_b128 v[216:219], v183 offset:56320
	global_load_lds_dwordx4 v[220:221], off
	s_add_i32 m0, s16, 0x2000
	s_add_u32 s14, s14, 0x100080
	v_lshl_add_u64 v[220:221], v[222:223], 0, s[28:29]
	s_addc_u32 s15, s15, 0
	s_add_i32 s16, s22, s37
	global_load_lds_dwordx4 v[220:221], off
	v_lshl_add_u64 v[220:221], s[14:15], 0, v[130:131]
	s_mov_b32 m0, s16
	s_nop 0
	global_load_lds_dwordx4 v[220:221], off
	v_lshl_add_u64 v[220:221], s[14:15], 0, v[134:135]
	s_add_i32 m0, s16, 0x2000
	s_nop 0
	global_load_lds_dwordx4 v[220:221], off
	v_lshl_add_u64 v[220:221], v[224:225], 0, s[28:29]
	s_mov_b32 m0, s27
	s_nop 0
	global_load_lds_dwordx4 v[220:221], off
	v_lshl_add_u64 v[220:221], v[226:227], 0, s[28:29]
	s_mov_b32 m0, s2
	s_nop 0
	global_load_lds_dwordx4 v[220:221], off
	s_waitcnt vmcnt(8)
	s_waitcnt lgkmcnt(0)
	s_barrier
	s_setprio 1
	v_mfma_f32_16x16x32_bf16 v[60:63], v[152:155], v[188:191], v[60:63]
	v_mfma_f32_16x16x32_bf16 v[56:59], v[160:163], v[188:191], v[56:59]
	v_mfma_f32_16x16x32_bf16 v[44:47], v[152:155], v[196:199], v[44:47]
	v_mfma_f32_16x16x32_bf16 v[40:43], v[160:163], v[196:199], v[40:43]
	v_mfma_f32_16x16x32_bf16 v[28:31], v[152:155], v[204:207], v[28:31]
	v_mfma_f32_16x16x32_bf16 v[24:27], v[160:163], v[204:207], v[24:27]
	v_mfma_f32_16x16x32_bf16 v[12:15], v[152:155], v[212:215], v[12:15]
	v_mfma_f32_16x16x32_bf16 v[8:11], v[160:163], v[212:215], v[8:11]
	v_mfma_f32_16x16x32_bf16 v[60:63], v[156:159], v[192:195], v[60:63]
	v_mfma_f32_16x16x32_bf16 v[56:59], v[164:167], v[192:195], v[56:59]
	v_mfma_f32_16x16x32_bf16 v[44:47], v[156:159], v[200:203], v[44:47]
	v_mfma_f32_16x16x32_bf16 v[40:43], v[164:167], v[200:203], v[40:43]
	v_mfma_f32_16x16x32_bf16 v[28:31], v[156:159], v[208:211], v[28:31]
	v_mfma_f32_16x16x32_bf16 v[24:27], v[164:167], v[208:211], v[24:27]
	v_mfma_f32_16x16x32_bf16 v[12:15], v[156:159], v[216:219], v[12:15]
	v_mfma_f32_16x16x32_bf16 v[8:11], v[164:167], v[216:219], v[8:11]
	v_mfma_f32_16x16x32_bf16 v[52:55], v[168:171], v[188:191], v[52:55]
	v_mfma_f32_16x16x32_bf16 v[48:51], v[176:179], v[188:191], v[48:51]
	v_mfma_f32_16x16x32_bf16 v[36:39], v[168:171], v[196:199], v[36:39]
	v_mfma_f32_16x16x32_bf16 v[32:35], v[176:179], v[196:199], v[32:35]
	v_mfma_f32_16x16x32_bf16 v[20:23], v[168:171], v[204:207], v[20:23]
	v_mfma_f32_16x16x32_bf16 v[16:19], v[176:179], v[204:207], v[16:19]
	v_mfma_f32_16x16x32_bf16 v[4:7], v[168:171], v[212:215], v[4:7]
	v_mfma_f32_16x16x32_bf16 v[0:3], v[176:179], v[212:215], v[0:3]
	v_mfma_f32_16x16x32_bf16 v[52:55], v[172:175], v[192:195], v[52:55]
	v_mfma_f32_16x16x32_bf16 v[48:51], v[184:187], v[192:195], v[48:51]
	v_mfma_f32_16x16x32_bf16 v[36:39], v[172:175], v[200:203], v[36:39]
	v_mfma_f32_16x16x32_bf16 v[32:35], v[184:187], v[200:203], v[32:35]
	v_mfma_f32_16x16x32_bf16 v[20:23], v[172:175], v[208:211], v[20:23]
	v_mfma_f32_16x16x32_bf16 v[16:19], v[184:187], v[208:211], v[16:19]
	v_mfma_f32_16x16x32_bf16 v[4:7], v[172:175], v[216:219], v[4:7]
	v_mfma_f32_16x16x32_bf16 v[0:3], v[184:187], v[216:219], v[0:3]
	s_setprio 0
	s_barrier
	s_add_i32 s20, s20, 2
	s_add_u32 s12, s12, 0x100
	s_addc_u32 s13, s13, 0
	s_add_u32 s7, s7, 0x100
	s_addc_u32 s11, s11, 0
	s_cmp_gt_u32 s20, 61
	s_cbranch_scc0 .LBB0_1759
	v_readlane_b32 s4, v250, 18
	v_readlane_b32 s5, v250, 19
	s_and_b64 vcc, exec, s[4:5]
	s_cbranch_vccz .LBB0_1762
	s_barrier

; #define PG8_STAGE(bufoff, gbase, voff) do { _Pragma("unroll") for (int _i = 0; _i < 2; ++_i) \
;         __builtin_amdgcn_global_load_lds((const unsigned*)((const char*)(gbase) + (voff)[_i]), (PG8_LAS unsigned*)(lds + (bufoff) + ldsw + _i * 8192), 16, 0, 0); } while (0)
; #define PG8_LDA(dst, b, h) do { _Pragma("unroll") for (int m = 0; m < 4; ++m) _Pragma("unroll") for (int k = 0; k < 2; ++k) dst[m][k] = *(const PG8_LAS bf16x8*)(lds + PG8_SA(b, h) + aoff + m * 2048 + k * 1024); } while (0)
; #define PG8_LDB(dst, b, h) do { _Pragma("unroll") for (int n = 0; n < 2; ++n) _Pragma("unroll") for (int k = 0; k < 2; ++k) dst[n][k] = *(const PG8_LAS bf16x8*)(lds + PG8_SB(b, h) + boff + n * 2048 + k * 1024); } while (0)
; #define PG8_MMA(ai, bj, At, Bt) do { __builtin_amdgcn_s_setprio(1); _Pragma("unroll") for (int m = 0; m < 4; ++m) _Pragma("unroll") for (int n = 0; n < 2; ++n) _Pragma("unroll") for (int k = 0; k < 2; ++k) \
;         acc[ai][bj][m][n] = __builtin_amdgcn_mfma_f32_16x16x32_bf16(Bt[n][k], At[m][k], acc[ai][bj][m][n], 0, 0, 0); __builtin_amdgcn_s_setprio(0); } while (0)
; #define PG8_WAIT_V(n) asm volatile("s_waitcnt vmcnt(" #n ")" ::: "memory")
; #define PG8_WAIT_L(n) asm volatile("s_waitcnt lgkmcnt(" #n ")" ::: "memory")
; #define PG8_BAR __builtin_amdgcn_s_barrier()
; template <class Epi, class Sched, bool ALIGN_EPI = false, bool SP2 = false>
; __device__ __forceinline__ void gemm_phase(PG8_LAS unsigned char* lds, const Gemm g, const Sched& S, const Epi& E, const int tid_in) {
;     ...
;             const char* a1 = cA + (size_t)(t + 1) * kstep;
;             const char* a2 = last ? nA : cA + (size_t)(t + 2) * kstep; const char* b2 = last ? nB : cB + (size_t)(t + 2) * kstep;
;             const char* a3 = a2 + kstep; const char* b3 = b2 + kstep;
;             if (last && has_next) S.a_ready(nxt);
;             if constexpr (SP2) {
;             PG8_LDB(B0, 0, 0); PG8_LDB(B1, 0, 1); PG8_SCHED; PG8_LDA(At, 0, 0); PG8_STAGE(PG8_SA(1, 1), a1 + hstep, voffA);
;             PG8_WAIT_V(8); PG8_WAIT_L(0); PG8_BAR; PG8_MMA(0, 0, At, B0); PG8_MMA(0, 1, At, B1); PG8_BAR; PG8_SCHED;
;             PG8_LDA(At, 0, 1); PG8_STAGE(PG8_SB(0, 0), b2, voffB); PG8_STAGE(PG8_SB(0, 1), b2 + hstep, voffB); PG8_STAGE(PG8_SA(0, 0), a2, voffA);
;             PG8_WAIT_V(8); PG8_WAIT_L(0); PG8_BAR; PG8_MMA(1, 0, At, B0); PG8_MMA(1, 1, At, B1); PG8_BAR; PG8_SCHED;
.LBB0_3063:
	ds_read_b128 v[128:131], v171
	ds_read_b128 v[132:135], v171 offset:1024
	ds_read_b128 v[136:139], v171 offset:2048
	ds_read_b128 v[140:143], v171 offset:3072
	ds_read_b128 v[160:163], v172
	ds_read_b128 v[174:177], v172 offset:1024
	ds_read_b128 v[178:181], v172 offset:2048
	ds_read_b128 v[182:185], v172 offset:3072
	s_add_u32 s26, s24, 0xfff00080
	s_addc_u32 s27, s25, -1
	s_cmp_eq_u32 s53, 60
	s_cselect_b32 s29, s17, s27
	s_cselect_b32 s28, s49, s26
	s_cselect_b32 s27, s15, s52
	s_cselect_b32 s26, s50, s51
	v_lshl_add_u64 v[164:165], s[24:25], 0, v[152:153]
	s_add_i32 m0, s23, 0xc000
	ds_read_b128 v[186:189], v173
	ds_read_b128 v[190:193], v173 offset:1024
	ds_read_b128 v[194:197], v173 offset:2048
	ds_read_b128 v[198:201], v173 offset:3072
	ds_read_b128 v[202:205], v173 offset:4096
	ds_read_b128 v[206:209], v173 offset:5120
	ds_read_b128 v[210:213], v173 offset:6144
	ds_read_b128 v[214:217], v173 offset:7168
	global_load_lds_dwordx4 v[164:165], off
	v_lshl_add_u64 v[164:165], s[24:25], 0, v[154:155]
	s_add_i32 m0, s23, 0xe000
	s_nop 0
	global_load_lds_dwordx4 v[164:165], off
	s_waitcnt vmcnt(8)
	s_waitcnt lgkmcnt(0)
	s_barrier
	s_setprio 1
	v_mfma_f32_16x16x32_bf16 v[124:127], v[128:131], v[186:189], v[124:127]
	v_mfma_f32_16x16x32_bf16 v[120:123], v[136:139], v[186:189], v[120:123]
	v_mfma_f32_16x16x32_bf16 v[116:119], v[128:131], v[194:197], v[116:119]
	v_mfma_f32_16x16x32_bf16 v[112:115], v[136:139], v[194:197], v[112:115]
	v_mfma_f32_16x16x32_bf16 v[92:95], v[128:131], v[202:205], v[92:95]
	v_mfma_f32_16x16x32_bf16 v[88:91], v[136:139], v[202:205], v[88:91]
	v_mfma_f32_16x16x32_bf16 v[84:87], v[128:131], v[210:213], v[84:87]
	v_mfma_f32_16x16x32_bf16 v[80:83], v[136:139], v[210:213], v[80:83]
	v_mfma_f32_16x16x32_bf16 v[124:127], v[132:135], v[190:193], v[124:127]
	v_mfma_f32_16x16x32_bf16 v[120:123], v[140:143], v[190:193], v[120:123]
	v_mfma_f32_16x16x32_bf16 v[116:119], v[132:135], v[198:201], v[116:119]
	v_mfma_f32_16x16x32_bf16 v[112:115], v[140:143], v[198:201], v[112:115]
	v_mfma_f32_16x16x32_bf16 v[92:95], v[132:135], v[206:209], v[92:95]
	v_mfma_f32_16x16x32_bf16 v[88:91], v[140:143], v[206:209], v[88:91]
	v_mfma_f32_16x16x32_bf16 v[84:87], v[132:135], v[214:217], v[84:87]
	v_mfma_f32_16x16x32_bf16 v[80:83], v[140:143], v[214:217], v[80:83]
	v_mfma_f32_16x16x32_bf16 v[108:111], v[160:163], v[186:189], v[108:111]
	v_mfma_f32_16x16x32_bf16 v[104:107], v[178:181], v[186:189], v[104:107]
	v_mfma_f32_16x16x32_bf16 v[100:103], v[160:163], v[194:197], v[100:103]
	v_mfma_f32_16x16x32_bf16 v[96:99], v[178:181], v[194:197], v[96:99]
	v_mfma_f32_16x16x32_bf16 v[76:79], v[160:163], v[202:205], v[76:79]
	v_mfma_f32_16x16x32_bf16 v[72:75], v[178:181], v[202:205], v[72:75]
	v_mfma_f32_16x16x32_bf16 v[68:71], v[160:163], v[210:213], v[68:71]
	v_mfma_f32_16x16x32_bf16 v[64:67], v[178:181], v[210:213], v[64:67]
	v_mfma_f32_16x16x32_bf16 v[108:111], v[174:177], v[190:193], v[108:111]
	v_mfma_f32_16x16x32_bf16 v[104:107], v[182:185], v[190:193], v[104:107]
	v_mfma_f32_16x16x32_bf16 v[100:103], v[174:177], v[198:201], v[100:103]
	v_mfma_f32_16x16x32_bf16 v[96:99], v[182:185], v[198:201], v[96:99]
	v_mfma_f32_16x16x32_bf16 v[76:79], v[174:177], v[206:209], v[76:79]
	v_mfma_f32_16x16x32_bf16 v[72:75], v[182:185], v[206:209], v[72:75]
	v_mfma_f32_16x16x32_bf16 v[68:71], v[174:177], v[214:217], v[68:71]
	v_mfma_f32_16x16x32_bf16 v[64:67], v[182:185], v[214:217], v[64:67]
	s_setprio 0
	s_barrier
	s_add_i32 s54, s45, s37
	v_lshl_add_u64 v[164:165], s[26:27], 0, v[148:149]
	s_mov_b32 m0, s54
	ds_read_b128 v[186:189], v173 offset:16384
	ds_read_b128 v[190:193], v173 offset:17408
	ds_read_b128 v[194:197], v173 offset:18432
	ds_read_b128 v[198:201], v173 offset:19456
	ds_read_b128 v[202:205], v173 offset:20480
	ds_read_b128 v[206:209], v173 offset:21504
	ds_read_b128 v[210:213], v173 offset:22528
	ds_read_b128 v[214:217], v173 offset:23552
	global_load_lds_dwordx4 v[164:165], off
	s_add_i32 m0, s54, 0x2000
	s_add_u32 s54, s26, 0x100000
	v_lshl_add_u64 v[218:219], s[26:27], 0, v[144:145]
	s_addc_u32 s55, s27, 0
	s_add_i32 s56, s46, s37
	global_load_lds_dwordx4 v[218:219], off
	v_lshl_add_u64 v[220:221], s[54:55], 0, v[148:149]
	s_mov_b32 m0, s56
	v_lshl_add_u64 v[222:223], s[28:29], 0, v[146:147]
	global_load_lds_dwordx4 v[220:221], off
	v_lshl_add_u64 v[220:221], s[54:55], 0, v[144:145]
	s_add_i32 m0, s56, 0x2000
	s_nop 0
	global_load_lds_dwordx4 v[220:221], off
	v_lshl_add_u64 v[220:221], s[28:29], 0, v[150:151]
	s_mov_b32 m0, s23
	s_nop 0
	global_load_lds_dwordx4 v[220:221], off
	s_mov_b32 m0, s38
	s_nop 0
	global_load_lds_dwordx4 v[222:223], off
	s_waitcnt vmcnt(8)
	s_waitcnt lgkmcnt(0)
	s_barrier
; #define PG8_STAGE(bufoff, gbase, voff) do { _Pragma("unroll") for (int _i = 0; _i < 2; ++_i) \
;         __builtin_amdgcn_global_load_lds((const unsigned*)((const char*)(gbase) + (voff)[_i]), (PG8_LAS unsigned*)(lds + (bufoff) + ldsw + _i * 8192), 16, 0, 0); } while (0)
; #define PG8_LDA(dst, b, h) do { _Pragma("unroll") for (int m = 0; m < 4; ++m) _Pragma("unroll") for (int k = 0; k < 2; ++k) dst[m][k] = *(const PG8_LAS bf16x8*)(lds + PG8_SA(b, h) + aoff + m * 2048 + k * 1024); } while (0)
; #define PG8_LDB(dst, b, h) do { _Pragma("unroll") for (int n = 0; n < 2; ++n) _Pragma("unroll") for (int k = 0; k < 2; ++k) dst[n][k] = *(const PG8_LAS bf16x8*)(lds + PG8_SB(b, h) + boff + n * 2048 + k * 1024); } while (0)
; #define PG8_MMA(ai, bj, At, Bt) do { __builtin_amdgcn_s_setprio(1); _Pragma("unroll") for (int m = 0; m < 4; ++m) _Pragma("unroll") for (int n = 0; n < 2; ++n) _Pragma("unroll") for (int k = 0; k < 2; ++k) \
;         acc[ai][bj][m][n] = __builtin_amdgcn_mfma_f32_16x16x32_bf16(Bt[n][k], At[m][k], acc[ai][bj][m][n], 0, 0, 0); __builtin_amdgcn_s_setprio(0); } while (0)
; #define PG8_WAIT_V(n) asm volatile("s_waitcnt vmcnt(" #n ")" ::: "memory")
; #define PG8_WAIT_L(n) asm volatile("s_waitcnt lgkmcnt(" #n ")" ::: "memory")
; #define PG8_BAR __builtin_amdgcn_s_barrier()
; #define PG8_SCHED __builtin_amdgcn_sched_barrier(0)
; template <class Epi, class Sched, bool ALIGN_EPI = false, bool SP2 = false>
; __device__ __forceinline__ void gemm_phase(PG8_LAS unsigned char* lds, const Gemm g, const Sched& S, const Epi& E, const int tid_in) {
;     ...
;             PG8_WAIT_V(8); PG8_WAIT_L(0); PG8_BAR; PG8_MMA(1, 0, At, B0); PG8_MMA(1, 1, At, B1); PG8_BAR; PG8_SCHED;
;             PG8_LDB(B0, 1, 0); PG8_LDB(B1, 1, 1); PG8_SCHED; PG8_LDA(At, 1, 0); PG8_STAGE(PG8_SA(0, 1), a2 + hstep, voffA);
;             PG8_WAIT_V(8); PG8_WAIT_L(0); PG8_BAR; PG8_MMA(0, 0, At, B0); PG8_MMA(0, 1, At, B1); PG8_BAR; PG8_SCHED;
	s_setprio 1
	v_mfma_f32_16x16x32_bf16 v[60:63], v[128:131], v[186:189], v[60:63]
	v_mfma_f32_16x16x32_bf16 v[56:59], v[136:139], v[186:189], v[56:59]
	v_mfma_f32_16x16x32_bf16 v[52:55], v[128:131], v[194:197], v[52:55]
	v_mfma_f32_16x16x32_bf16 v[48:51], v[136:139], v[194:197], v[48:51]
	v_mfma_f32_16x16x32_bf16 v[28:31], v[128:131], v[202:205], v[28:31]
	v_mfma_f32_16x16x32_bf16 v[24:27], v[136:139], v[202:205], v[24:27]
	v_mfma_f32_16x16x32_bf16 v[20:23], v[128:131], v[210:213], v[20:23]
	v_mfma_f32_16x16x32_bf16 v[16:19], v[136:139], v[210:213], v[16:19]
	v_mfma_f32_16x16x32_bf16 v[60:63], v[132:135], v[190:193], v[60:63]
	v_mfma_f32_16x16x32_bf16 v[56:59], v[140:143], v[190:193], v[56:59]
	v_mfma_f32_16x16x32_bf16 v[52:55], v[132:135], v[198:201], v[52:55]
	v_mfma_f32_16x16x32_bf16 v[48:51], v[140:143], v[198:201], v[48:51]
	v_mfma_f32_16x16x32_bf16 v[28:31], v[132:135], v[206:209], v[28:31]
	v_mfma_f32_16x16x32_bf16 v[24:27], v[140:143], v[206:209], v[24:27]
	v_mfma_f32_16x16x32_bf16 v[20:23], v[132:135], v[214:217], v[20:23]
	v_mfma_f32_16x16x32_bf16 v[16:19], v[140:143], v[214:217], v[16:19]
	v_mfma_f32_16x16x32_bf16 v[44:47], v[160:163], v[186:189], v[44:47]
	v_mfma_f32_16x16x32_bf16 v[40:43], v[178:181], v[186:189], v[40:43]
	v_mfma_f32_16x16x32_bf16 v[36:39], v[160:163], v[194:197], v[36:39]
	v_mfma_f32_16x16x32_bf16 v[32:35], v[178:181], v[194:197], v[32:35]
	v_mfma_f32_16x16x32_bf16 v[12:15], v[160:163], v[202:205], v[12:15]
	v_mfma_f32_16x16x32_bf16 v[8:11], v[178:181], v[202:205], v[8:11]
	v_mfma_f32_16x16x32_bf16 v[4:7], v[160:163], v[210:213], v[4:7]
	v_mfma_f32_16x16x32_bf16 v[0:3], v[178:181], v[210:213], v[0:3]
	v_mfma_f32_16x16x32_bf16 v[44:47], v[174:177], v[190:193], v[44:47]
	v_mfma_f32_16x16x32_bf16 v[40:43], v[182:185], v[190:193], v[40:43]
	v_mfma_f32_16x16x32_bf16 v[36:39], v[174:177], v[198:201], v[36:39]
	v_mfma_f32_16x16x32_bf16 v[32:35], v[182:185], v[198:201], v[32:35]
	v_mfma_f32_16x16x32_bf16 v[12:15], v[174:177], v[206:209], v[12:15]
	v_mfma_f32_16x16x32_bf16 v[8:11], v[182:185], v[206:209], v[8:11]
	v_mfma_f32_16x16x32_bf16 v[4:7], v[174:177], v[214:217], v[4:7]
	v_mfma_f32_16x16x32_bf16 v[0:3], v[182:185], v[214:217], v[0:3]
	s_setprio 0
	s_barrier
	s_add_i32 s54, 0, 0x18000
	s_add_i32 s55, 0, 0x1c000
	v_add_u32_e32 v140, s54, v169
	v_add_u32_e32 v182, s55, v169
	ds_read_b128 v[128:131], v140
	ds_read_b128 v[132:135], v140 offset:1024
	ds_read_b128 v[136:139], v140 offset:2048
	ds_read_b128 v[140:143], v140 offset:3072
	ds_read_b128 v[160:163], v182
	ds_read_b128 v[174:177], v182 offset:1024
	ds_read_b128 v[178:181], v182 offset:2048
	ds_read_b128 v[182:185], v182 offset:3072
	s_add_u32 s28, s28, 0x100000
	s_addc_u32 s29, s29, 0
	s_mov_b32 m0, s39
	v_lshl_add_u64 v[224:225], s[28:29], 0, v[150:151]
	ds_read_b128 v[186:189], v173 offset:32768
	ds_read_b128 v[190:193], v173 offset:33792
	ds_read_b128 v[194:197], v173 offset:34816
	ds_read_b128 v[198:201], v173 offset:35840
	ds_read_b128 v[202:205], v173 offset:36864
	ds_read_b128 v[206:209], v173 offset:37888
	ds_read_b128 v[210:213], v173 offset:38912
	ds_read_b128 v[214:217], v173 offset:39936
	global_load_lds_dwordx4 v[224:225], off
	v_lshl_add_u64 v[224:225], s[28:29], 0, v[146:147]
	s_mov_b32 m0, s40
	s_nop 0
	global_load_lds_dwordx4 v[224:225], off
	s_waitcnt vmcnt(8)
	s_waitcnt lgkmcnt(0)
	s_barrier
	s_setprio 1
	v_mfma_f32_16x16x32_bf16 v[124:127], v[128:131], v[186:189], v[124:127]
	v_mfma_f32_16x16x32_bf16 v[120:123], v[136:139], v[186:189], v[120:123]
	v_mfma_f32_16x16x32_bf16 v[116:119], v[128:131], v[194:197], v[116:119]
	v_mfma_f32_16x16x32_bf16 v[112:115], v[136:139], v[194:197], v[112:115]
	v_mfma_f32_16x16x32_bf16 v[92:95], v[128:131], v[202:205], v[92:95]
	v_mfma_f32_16x16x32_bf16 v[88:91], v[136:139], v[202:205], v[88:91]
	v_mfma_f32_16x16x32_bf16 v[84:87], v[128:131], v[210:213], v[84:87]
	v_mfma_f32_16x16x32_bf16 v[80:83], v[136:139], v[210:213], v[80:83]
	v_mfma_f32_16x16x32_bf16 v[124:127], v[132:135], v[190:193], v[124:127]
	v_mfma_f32_16x16x32_bf16 v[120:123], v[140:143], v[190:193], v[120:123]
	v_mfma_f32_16x16x32_bf16 v[116:119], v[132:135], v[198:201], v[116:119]
	v_mfma_f32_16x16x32_bf16 v[112:115], v[140:143], v[198:201], v[112:115]
	v_mfma_f32_16x16x32_bf16 v[92:95], v[132:135], v[206:209], v[92:95]
	v_mfma_f32_16x16x32_bf16 v[88:91], v[140:143], v[206:209], v[88:91]
	v_mfma_f32_16x16x32_bf16 v[84:87], v[132:135], v[214:217], v[84:87]
	v_mfma_f32_16x16x32_bf16 v[80:83], v[140:143], v[214:217], v[80:83]
	v_mfma_f32_16x16x32_bf16 v[108:111], v[160:163], v[186:189], v[108:111]
	v_mfma_f32_16x16x32_bf16 v[104:107], v[178:181], v[186:189], v[104:107]
	v_mfma_f32_16x16x32_bf16 v[100:103], v[160:163], v[194:197], v[100:103]
	v_mfma_f32_16x16x32_bf16 v[96:99], v[178:181], v[194:197], v[96:99]
	v_mfma_f32_16x16x32_bf16 v[76:79], v[160:163], v[202:205], v[76:79]
	v_mfma_f32_16x16x32_bf16 v[72:75], v[178:181], v[202:205], v[72:75]
	v_mfma_f32_16x16x32_bf16 v[68:71], v[160:163], v[210:213], v[68:71]
	v_mfma_f32_16x16x32_bf16 v[64:67], v[178:181], v[210:213], v[64:67]
	v_mfma_f32_16x16x32_bf16 v[108:111], v[174:177], v[190:193], v[108:111]
	v_mfma_f32_16x16x32_bf16 v[104:107], v[182:185], v[190:193], v[104:107]
	v_mfma_f32_16x16x32_bf16 v[100:103], v[174:177], v[198:201], v[100:103]
	v_mfma_f32_16x16x32_bf16 v[96:99], v[182:185], v[198:201], v[96:99]
	v_mfma_f32_16x16x32_bf16 v[76:79], v[174:177], v[206:209], v[76:79]
	v_mfma_f32_16x16x32_bf16 v[72:75], v[182:185], v[206:209], v[72:75]
	v_mfma_f32_16x16x32_bf16 v[68:71], v[174:177], v[214:217], v[68:71]
	v_mfma_f32_16x16x32_bf16 v[64:67], v[182:185], v[214:217], v[64:67]
	s_setprio 0
	s_barrier
; #define PG8_STAGE(bufoff, gbase, voff) do { _Pragma("unroll") for (int _i = 0; _i < 2; ++_i) \
;         __builtin_amdgcn_global_load_lds((const unsigned*)((const char*)(gbase) + (voff)[_i]), (PG8_LAS unsigned*)(lds + (bufoff) + ldsw + _i * 8192), 16, 0, 0); } while (0)
; #define PG8_LDA(dst, b, h) do { _Pragma("unroll") for (int m = 0; m < 4; ++m) _Pragma("unroll") for (int k = 0; k < 2; ++k) dst[m][k] = *(const PG8_LAS bf16x8*)(lds + PG8_SA(b, h) + aoff + m * 2048 + k * 1024); } while (0)
; #define PG8_MMA(ai, bj, At, Bt) do { __builtin_amdgcn_s_setprio(1); _Pragma("unroll") for (int m = 0; m < 4; ++m) _Pragma("unroll") for (int n = 0; n < 2; ++n) _Pragma("unroll") for (int k = 0; k < 2; ++k) \
;         acc[ai][bj][m][n] = __builtin_amdgcn_mfma_f32_16x16x32_bf16(Bt[n][k], At[m][k], acc[ai][bj][m][n], 0, 0, 0); __builtin_amdgcn_s_setprio(0); } while (0)
; #define PG8_WAIT_V(n) asm volatile("s_waitcnt vmcnt(" #n ")" ::: "memory")
; #define PG8_WAIT_L(n) asm volatile("s_waitcnt lgkmcnt(" #n ")" ::: "memory")
; #define PG8_BAR __builtin_amdgcn_s_barrier()
; #define PG8_SCHED __builtin_amdgcn_sched_barrier(0)
; template <class Epi, class Sched, bool ALIGN_EPI = false, bool SP2 = false>
; __device__ __forceinline__ void gemm_phase(PG8_LAS unsigned char* lds, const Gemm g, const Sched& S, const Epi& E, const int tid_in) {
;     ...
;             PG8_LDA(At, 1, 1); PG8_STAGE(PG8_SB(1, 0), b3, voffB); PG8_STAGE(PG8_SB(1, 1), b3 + hstep, voffB); PG8_STAGE(PG8_SA(1, 0), a3, voffA);
;             PG8_WAIT_V(8); PG8_WAIT_L(0); PG8_BAR; PG8_MMA(1, 0, At, B0); PG8_MMA(1, 1, At, B1); PG8_BAR; PG8_SCHED;
	s_add_i32 s28, s54, s37
	v_lshl_add_u64 v[164:165], v[164:165], 0, s[8:9]
	s_mov_b32 m0, s28
	ds_read_b128 v[186:189], v173 offset:49152
	ds_read_b128 v[190:193], v173 offset:50176
	ds_read_b128 v[194:197], v173 offset:51200
	ds_read_b128 v[198:201], v173 offset:52224
	ds_read_b128 v[202:205], v173 offset:53248
	ds_read_b128 v[206:209], v173 offset:54272
	ds_read_b128 v[210:213], v173 offset:55296
	ds_read_b128 v[214:217], v173 offset:56320
	global_load_lds_dwordx4 v[164:165], off
	s_add_i32 m0, s28, 0x2000
	s_add_u32 s26, s26, 0x100080
	v_lshl_add_u64 v[164:165], v[218:219], 0, s[8:9]
	s_addc_u32 s27, s27, 0
	s_add_i32 s28, s55, s37
	global_load_lds_dwordx4 v[164:165], off
	v_lshl_add_u64 v[164:165], s[26:27], 0, v[148:149]
	s_mov_b32 m0, s28
	s_nop 0
	global_load_lds_dwordx4 v[164:165], off
	v_lshl_add_u64 v[164:165], s[26:27], 0, v[144:145]
	s_add_i32 m0, s28, 0x2000
	s_nop 0
	global_load_lds_dwordx4 v[164:165], off
	v_lshl_add_u64 v[164:165], v[220:221], 0, s[8:9]
	s_mov_b32 m0, s43
	s_nop 0
	global_load_lds_dwordx4 v[164:165], off
	v_lshl_add_u64 v[164:165], v[222:223], 0, s[8:9]
	s_mov_b32 m0, s44
	s_nop 0
	global_load_lds_dwordx4 v[164:165], off
	s_waitcnt vmcnt(8)
	s_waitcnt lgkmcnt(0)
	s_barrier
	s_setprio 1
	v_mfma_f32_16x16x32_bf16 v[60:63], v[128:131], v[186:189], v[60:63]
	v_mfma_f32_16x16x32_bf16 v[56:59], v[136:139], v[186:189], v[56:59]
	v_mfma_f32_16x16x32_bf16 v[52:55], v[128:131], v[194:197], v[52:55]
	v_mfma_f32_16x16x32_bf16 v[48:51], v[136:139], v[194:197], v[48:51]
	v_mfma_f32_16x16x32_bf16 v[28:31], v[128:131], v[202:205], v[28:31]
	v_mfma_f32_16x16x32_bf16 v[24:27], v[136:139], v[202:205], v[24:27]
	v_mfma_f32_16x16x32_bf16 v[20:23], v[128:131], v[210:213], v[20:23]
	v_mfma_f32_16x16x32_bf16 v[16:19], v[136:139], v[210:213], v[16:19]
	v_mfma_f32_16x16x32_bf16 v[60:63], v[132:135], v[190:193], v[60:63]
	v_mfma_f32_16x16x32_bf16 v[56:59], v[140:143], v[190:193], v[56:59]
	v_mfma_f32_16x16x32_bf16 v[52:55], v[132:135], v[198:201], v[52:55]
	v_mfma_f32_16x16x32_bf16 v[48:51], v[140:143], v[198:201], v[48:51]
	v_mfma_f32_16x16x32_bf16 v[28:31], v[132:135], v[206:209], v[28:31]
	v_mfma_f32_16x16x32_bf16 v[24:27], v[140:143], v[206:209], v[24:27]
	v_mfma_f32_16x16x32_bf16 v[20:23], v[132:135], v[214:217], v[20:23]
	v_mfma_f32_16x16x32_bf16 v[16:19], v[140:143], v[214:217], v[16:19]
	v_mfma_f32_16x16x32_bf16 v[44:47], v[160:163], v[186:189], v[44:47]
	v_mfma_f32_16x16x32_bf16 v[40:43], v[178:181], v[186:189], v[40:43]
	v_mfma_f32_16x16x32_bf16 v[36:39], v[160:163], v[194:197], v[36:39]
	v_mfma_f32_16x16x32_bf16 v[32:35], v[178:181], v[194:197], v[32:35]
	v_mfma_f32_16x16x32_bf16 v[12:15], v[160:163], v[202:205], v[12:15]
	v_mfma_f32_16x16x32_bf16 v[8:11], v[178:181], v[202:205], v[8:11]
	v_mfma_f32_16x16x32_bf16 v[4:7], v[160:163], v[210:213], v[4:7]
	v_mfma_f32_16x16x32_bf16 v[0:3], v[178:181], v[210:213], v[0:3]
	v_mfma_f32_16x16x32_bf16 v[44:47], v[174:177], v[190:193], v[44:47]
	v_mfma_f32_16x16x32_bf16 v[40:43], v[182:185], v[190:193], v[40:43]
	v_mfma_f32_16x16x32_bf16 v[36:39], v[174:177], v[198:201], v[36:39]
	v_mfma_f32_16x16x32_bf16 v[32:35], v[182:185], v[198:201], v[32:35]
	v_mfma_f32_16x16x32_bf16 v[12:15], v[174:177], v[206:209], v[12:15]
	v_mfma_f32_16x16x32_bf16 v[8:11], v[182:185], v[206:209], v[8:11]
	v_mfma_f32_16x16x32_bf16 v[4:7], v[174:177], v[214:217], v[4:7]
	v_mfma_f32_16x16x32_bf16 v[0:3], v[182:185], v[214:217], v[0:3]
	s_setprio 0
	s_barrier
	s_add_i32 s53, s53, 2
	s_add_u32 s24, s24, 0x100
	s_addc_u32 s25, s25, 0
	s_add_u32 s51, s51, 0x100
	s_addc_u32 s52, s52, 0
	s_cmp_gt_u32 s53, 61
	s_cbranch_scc0 .LBB0_3063
	s_and_b64 vcc, exec, s[10:11]
	s_cbranch_vccz .LBB0_3066
	s_barrier
